# cache policy: conv-gate phase's H stores non-temporal as well
# speedup vs baseline: 1.0105x; 1.0105x over previous
; __device__ __forceinline__ unsigned cvt_pk_bf16(float lo, float hi) { unsigned r; asm volatile("v_cvt_pk_bf16_f32 %0, %1, %2" : "=v"(r) : "v"(lo), "v"(hi)); return r; }
; __device__ __forceinline__ float bflo(unsigned w) { return __uint_as_float(w << 16); }
; __device__ __forceinline__ float bfhi(unsigned w) { return __uint_as_float(w & 0xffff0000u); }
; __device__ __forceinline__ void convgate_phase(const bf16_t* U, bf16_t* H, int rows, const float* ck, int gw, int NGW, int lane) {
;     for (int row = gw; row < rows; row += NGW) {
;         const bool lat = row < ML; const int t = lat ? (row & (SEQ - 1)) : ((row - ML) & (CL - 1)); const int L = lat ? SEQ : CL;
;         const bool hasp = t > 0, hasn = t < L - 1;
;         const bf16_t* ur = U + (size_t)row * 3072;
;         u32x4 bq[2], cq[2], vq[2], cp[2], vp[2], cn[2], vn[2];
; #pragma unroll
;         for (int hf = 0; hf < 2; ++hf) {
;             const int c0 = lane * 16 + hf * 8;
;             bq[hf] = *(const u32x4*)(ur + c0); cq[hf] = *(const u32x4*)(ur + 1024 + c0); vq[hf] = *(const u32x4*)(ur + 2048 + c0);
;             cp[hf] = (u32x4){0, 0, 0, 0}; vp[hf] = cp[hf]; cn[hf] = cp[hf]; vn[hf] = cp[hf];
;             if (hasp) { cp[hf] = *(const u32x4*)(ur - 3072 + 1024 + c0); vp[hf] = *(const u32x4*)(ur - 3072 + 2048 + c0); }
;             if (hasn) { cn[hf] = *(const u32x4*)(ur + 3072 + 1024 + c0); vn[hf] = *(const u32x4*)(ur + 3072 + 2048 + c0); }
;         }
; #pragma unroll
;         for (int hf = 0; hf < 2; ++hf) {
;             const int c0 = lane * 16 + hf * 8;
;             u32x4 ow;
; #pragma unroll
;             for (int e = 0; e < 4; ++e) {
;                 const f32x2 w0 = *(const f32x2*)(ck + c0 + 2 * e), w1 = *(const f32x2*)(ck + D + c0 + 2 * e), w2 = *(const f32x2*)(ck + 2 * D + c0 + 2 * e);
;                 const float lo = bflo(bq[hf][e]) * (w0[0] * (bflo(cp[hf][e]) * bflo(vp[hf][e])) + w1[0] * (bflo(cq[hf][e]) * bflo(vq[hf][e])) + w2[0] * (bflo(cn[hf][e]) * bflo(vn[hf][e])));
;                 const float hi = bfhi(bq[hf][e]) * (w0[1] * (bfhi(cp[hf][e]) * bfhi(vp[hf][e])) + w1[1] * (bfhi(cq[hf][e]) * bfhi(vq[hf][e])) + w2[1] * (bfhi(cn[hf][e]) * bfhi(vn[hf][e])));
;                 ow[e] = cvt_pk_bf16(lo, hi);
;             }
;             *(u32x4*)(H + (size_t)row * D + c0) = ow;
;         }
.Lcg9_nn0:
	v_lshlrev_b32_e32 v202, 16, v146
	v_and_b32_e32 v203, s14, v146
	v_pk_mul_f32 v[234:235], v[234:235], v[202:203]
	v_lshlrev_b32_e32 v206, 16, v147
	v_and_b32_e32 v207, s14, v147
	v_pk_mul_f32 v[236:237], v[236:237], v[206:207]
	v_lshlrev_b32_e32 v210, 16, v148
	v_and_b32_e32 v211, s14, v148
	v_pk_mul_f32 v[238:239], v[238:239], v[210:211]
	v_lshlrev_b32_e32 v202, 16, v149
	v_and_b32_e32 v203, s14, v149
	v_pk_mul_f32 v[240:241], v[240:241], v[202:203]
	v_lshlrev_b32_e32 v206, 16, v150
	v_and_b32_e32 v207, s14, v150
	v_pk_mul_f32 v[242:243], v[242:243], v[206:207]
	v_lshlrev_b32_e32 v210, 16, v151
	v_and_b32_e32 v211, s14, v151
	v_pk_mul_f32 v[244:245], v[244:245], v[210:211]
	v_lshlrev_b32_e32 v202, 16, v152
	v_and_b32_e32 v203, s14, v152
	v_pk_mul_f32 v[246:247], v[246:247], v[202:203]
	v_lshlrev_b32_e32 v206, 16, v153
	v_and_b32_e32 v207, s14, v153
	v_pk_mul_f32 v[248:249], v[248:249], v[206:207]
	v_cvt_pk_bf16_f32 v84, v234, v235
	v_cvt_pk_bf16_f32 v85, v236, v237
	v_cvt_pk_bf16_f32 v86, v238, v239
	v_cvt_pk_bf16_f32 v87, v240, v241
	v_cvt_pk_bf16_f32 v88, v242, v243
	v_cvt_pk_bf16_f32 v89, v244, v245
	v_cvt_pk_bf16_f32 v90, v246, v247
	v_cvt_pk_bf16_f32 v91, v248, v249
	global_store_dwordx4 v1, v[84:87], s[8:9] nt
	global_store_dwordx4 v1, v[88:91], s[8:9] offset:16 nt
	s_add_u32 s8, s8, 0x800
	s_addc_u32 s9, s9, 0
	global_load_dwordx4 v[146:149], v1, s[6:7]
	global_load_dwordx4 v[150:153], v1, s[6:7] offset:16
	s_add_u32 s6, s6, 0x1800
	s_addc_u32 s7, s7, 0
	s_waitcnt vmcnt(14)
	v_lshlrev_b32_e32 v202, 16, v114
	v_and_b32_e32 v203, s14, v114
	v_lshlrev_b32_e32 v204, 16, v122
	v_and_b32_e32 v205, s14, v122
	v_pk_mul_f32 v[52:53], v[202:203], v[204:205]
	v_lshlrev_b32_e32 v206, 16, v115
	v_and_b32_e32 v207, s14, v115
	v_lshlrev_b32_e32 v208, 16, v123
	v_and_b32_e32 v209, s14, v123
	v_pk_mul_f32 v[54:55], v[206:207], v[208:209]
	v_lshlrev_b32_e32 v210, 16, v116
	v_and_b32_e32 v211, s14, v116
	v_lshlrev_b32_e32 v212, 16, v124
	v_and_b32_e32 v213, s14, v124
	v_pk_mul_f32 v[56:57], v[210:211], v[212:213]
	v_lshlrev_b32_e32 v202, 16, v117
	v_and_b32_e32 v203, s14, v117
	v_lshlrev_b32_e32 v204, 16, v125
	v_and_b32_e32 v205, s14, v125
	v_pk_mul_f32 v[58:59], v[202:203], v[204:205]
	v_lshlrev_b32_e32 v206, 16, v118
	v_and_b32_e32 v207, s14, v118
	v_lshlrev_b32_e32 v208, 16, v126
	v_and_b32_e32 v209, s14, v126
	v_pk_mul_f32 v[60:61], v[206:207], v[208:209]
	v_lshlrev_b32_e32 v210, 16, v119
	v_and_b32_e32 v211, s14, v119
	v_lshlrev_b32_e32 v212, 16, v127
	v_and_b32_e32 v213, s14, v127
	v_pk_mul_f32 v[62:63], v[210:211], v[212:213]
	v_lshlrev_b32_e32 v202, 16, v120
	v_and_b32_e32 v203, s14, v120
	v_lshlrev_b32_e32 v204, 16, v128
	v_and_b32_e32 v205, s14, v128
	v_pk_mul_f32 v[64:65], v[202:203], v[204:205]
	v_lshlrev_b32_e32 v206, 16, v121
	v_and_b32_e32 v207, s14, v121
	v_lshlrev_b32_e32 v208, 16, v129
	v_and_b32_e32 v209, s14, v129
	v_pk_mul_f32 v[66:67], v[206:207], v[208:209]
	global_load_dwordx4 v[114:117], v1, s[4:5] offset:2048
	global_load_dwordx4 v[118:121], v1, s[4:5] offset:2064
	global_load_dwordx4 v[122:125], v2, s[4:5]
	global_load_dwordx4 v[126:129], v2, s[4:5] offset:16
	s_add_u32 s4, s4, 0x1800
	s_addc_u32 s5, s5, 0
	s_add_i32 s12, s11, 1
	s_cmp_lt_u32 s12, 0x4000
	s_cselect_b32 s29, s3, s13
	s_and_b32 s27, s12, s29
	v_pk_mul_f32 v[234:235], v[20:21], v[98:99]
	v_pk_mul_f32 v[236:237], v[22:23], v[100:101]
	v_pk_mul_f32 v[238:239], v[24:25], v[102:103]
	v_pk_mul_f32 v[240:241], v[26:27], v[104:105]
	v_pk_mul_f32 v[242:243], v[28:29], v[106:107]
	v_pk_mul_f32 v[244:245], v[30:31], v[108:109]
	v_pk_mul_f32 v[246:247], v[32:33], v[110:111]
	v_pk_mul_f32 v[248:249], v[34:35], v[112:113]
	s_cmp_eq_u32 s27, 0
	s_cbranch_scc1 .Lcg9_np1
	v_pk_fma_f32 v[234:235], v[4:5], v[68:69], v[234:235]
	v_pk_fma_f32 v[236:237], v[6:7], v[70:71], v[236:237]
	v_pk_fma_f32 v[238:239], v[8:9], v[72:73], v[238:239]
	v_pk_fma_f32 v[240:241], v[10:11], v[74:75], v[240:241]
	v_pk_fma_f32 v[242:243], v[12:13], v[76:77], v[242:243]
	v_pk_fma_f32 v[244:245], v[14:15], v[78:79], v[244:245]
	v_pk_fma_f32 v[246:247], v[16:17], v[80:81], v[246:247]
	v_pk_fma_f32 v[248:249], v[18:19], v[82:83], v[248:249]

; __device__ __forceinline__ unsigned cvt_pk_bf16(float lo, float hi) { unsigned r; asm volatile("v_cvt_pk_bf16_f32 %0, %1, %2" : "=v"(r) : "v"(lo), "v"(hi)); return r; }
; __device__ __forceinline__ float bflo(unsigned w) { return __uint_as_float(w << 16); }
; __device__ __forceinline__ float bfhi(unsigned w) { return __uint_as_float(w & 0xffff0000u); }
; __device__ __forceinline__ void convgate_phase(const bf16_t* U, bf16_t* H, int rows, const float* ck, int gw, int NGW, int lane) {
;     for (int row = gw; row < rows; row += NGW) {
;         const bool lat = row < ML; const int t = lat ? (row & (SEQ - 1)) : ((row - ML) & (CL - 1)); const int L = lat ? SEQ : CL;
;         const bool hasp = t > 0, hasn = t < L - 1;
;         const bf16_t* ur = U + (size_t)row * 3072;
;         u32x4 bq[2], cq[2], vq[2], cp[2], vp[2], cn[2], vn[2];
; #pragma unroll
;         for (int hf = 0; hf < 2; ++hf) {
;             const int c0 = lane * 16 + hf * 8;
;             bq[hf] = *(const u32x4*)(ur + c0); cq[hf] = *(const u32x4*)(ur + 1024 + c0); vq[hf] = *(const u32x4*)(ur + 2048 + c0);
;             cp[hf] = (u32x4){0, 0, 0, 0}; vp[hf] = cp[hf]; cn[hf] = cp[hf]; vn[hf] = cp[hf];
;             if (hasp) { cp[hf] = *(const u32x4*)(ur - 3072 + 1024 + c0); vp[hf] = *(const u32x4*)(ur - 3072 + 2048 + c0); }
;             if (hasn) { cn[hf] = *(const u32x4*)(ur + 3072 + 1024 + c0); vn[hf] = *(const u32x4*)(ur + 3072 + 2048 + c0); }
;         }
; #pragma unroll
;         for (int hf = 0; hf < 2; ++hf) {
;             const int c0 = lane * 16 + hf * 8;
;             u32x4 ow;
; #pragma unroll
;             for (int e = 0; e < 4; ++e) {
;                 const f32x2 w0 = *(const f32x2*)(ck + c0 + 2 * e), w1 = *(const f32x2*)(ck + D + c0 + 2 * e), w2 = *(const f32x2*)(ck + 2 * D + c0 + 2 * e);
;                 const float lo = bflo(bq[hf][e]) * (w0[0] * (bflo(cp[hf][e]) * bflo(vp[hf][e])) + w1[0] * (bflo(cq[hf][e]) * bflo(vq[hf][e])) + w2[0] * (bflo(cn[hf][e]) * bflo(vn[hf][e])));
;                 const float hi = bfhi(bq[hf][e]) * (w0[1] * (bfhi(cp[hf][e]) * bfhi(vp[hf][e])) + w1[1] * (bfhi(cq[hf][e]) * bfhi(vq[hf][e])) + w2[1] * (bfhi(cn[hf][e]) * bfhi(vn[hf][e])));
;                 ow[e] = cvt_pk_bf16(lo, hi);
;             }
;             *(u32x4*)(H + (size_t)row * D + c0) = ow;
;         }
.Lcg9_nn1:
	v_lshlrev_b32_e32 v202, 16, v176
	v_and_b32_e32 v203, s14, v176
	v_pk_mul_f32 v[234:235], v[234:235], v[202:203]
	v_lshlrev_b32_e32 v206, 16, v177
	v_and_b32_e32 v207, s14, v177
	v_pk_mul_f32 v[236:237], v[236:237], v[206:207]
	v_lshlrev_b32_e32 v210, 16, v178
	v_and_b32_e32 v211, s14, v178
	v_pk_mul_f32 v[238:239], v[238:239], v[210:211]
	v_lshlrev_b32_e32 v202, 16, v179
	v_and_b32_e32 v203, s14, v179
	v_pk_mul_f32 v[240:241], v[240:241], v[202:203]
	v_lshlrev_b32_e32 v206, 16, v180
	v_and_b32_e32 v207, s14, v180
	v_pk_mul_f32 v[242:243], v[242:243], v[206:207]
	v_lshlrev_b32_e32 v210, 16, v181
	v_and_b32_e32 v211, s14, v181
	v_pk_mul_f32 v[244:245], v[244:245], v[210:211]
	v_lshlrev_b32_e32 v202, 16, v182
	v_and_b32_e32 v203, s14, v182
	v_pk_mul_f32 v[246:247], v[246:247], v[202:203]
	v_lshlrev_b32_e32 v206, 16, v183
	v_and_b32_e32 v207, s14, v183
	v_pk_mul_f32 v[248:249], v[248:249], v[206:207]
	v_cvt_pk_bf16_f32 v84, v234, v235
	v_cvt_pk_bf16_f32 v85, v236, v237
	v_cvt_pk_bf16_f32 v86, v238, v239
	v_cvt_pk_bf16_f32 v87, v240, v241
	v_cvt_pk_bf16_f32 v88, v242, v243
	v_cvt_pk_bf16_f32 v89, v244, v245
	v_cvt_pk_bf16_f32 v90, v246, v247
	v_cvt_pk_bf16_f32 v91, v248, v249
	global_store_dwordx4 v1, v[84:87], s[8:9] nt
	global_store_dwordx4 v1, v[88:91], s[8:9] offset:16 nt
	s_add_u32 s8, s8, 0x800
	s_addc_u32 s9, s9, 0
	global_load_dwordx4 v[176:179], v1, s[6:7]
	global_load_dwordx4 v[180:183], v1, s[6:7] offset:16
	s_add_u32 s6, s6, 0x1800
	s_addc_u32 s7, s7, 0
	s_waitcnt vmcnt(16)
	v_lshlrev_b32_e32 v202, 16, v130
	v_and_b32_e32 v203, s14, v130
	v_lshlrev_b32_e32 v204, 16, v138
	v_and_b32_e32 v205, s14, v138
	v_pk_mul_f32 v[68:69], v[202:203], v[204:205]
	v_lshlrev_b32_e32 v206, 16, v131
	v_and_b32_e32 v207, s14, v131
	v_lshlrev_b32_e32 v208, 16, v139
	v_and_b32_e32 v209, s14, v139
	v_pk_mul_f32 v[70:71], v[206:207], v[208:209]
	v_lshlrev_b32_e32 v210, 16, v132
	v_and_b32_e32 v211, s14, v132
	v_lshlrev_b32_e32 v212, 16, v140
	v_and_b32_e32 v213, s14, v140
	v_pk_mul_f32 v[72:73], v[210:211], v[212:213]
	v_lshlrev_b32_e32 v202, 16, v133
	v_and_b32_e32 v203, s14, v133
	v_lshlrev_b32_e32 v204, 16, v141
	v_and_b32_e32 v205, s14, v141
	v_pk_mul_f32 v[74:75], v[202:203], v[204:205]
	v_lshlrev_b32_e32 v206, 16, v134
	v_and_b32_e32 v207, s14, v134
	v_lshlrev_b32_e32 v208, 16, v142
	v_and_b32_e32 v209, s14, v142
	v_pk_mul_f32 v[76:77], v[206:207], v[208:209]
	v_lshlrev_b32_e32 v210, 16, v135
	v_and_b32_e32 v211, s14, v135
	v_lshlrev_b32_e32 v212, 16, v143
	v_and_b32_e32 v213, s14, v143
	v_pk_mul_f32 v[78:79], v[210:211], v[212:213]
	v_lshlrev_b32_e32 v202, 16, v136
	v_and_b32_e32 v203, s14, v136
	v_lshlrev_b32_e32 v204, 16, v144
	v_and_b32_e32 v205, s14, v144
	v_pk_mul_f32 v[80:81], v[202:203], v[204:205]
	v_lshlrev_b32_e32 v206, 16, v137
	v_and_b32_e32 v207, s14, v137
	v_lshlrev_b32_e32 v208, 16, v145
	v_and_b32_e32 v209, s14, v145
	v_pk_mul_f32 v[82:83], v[206:207], v[208:209]
	global_load_dwordx4 v[130:133], v1, s[4:5] offset:2048
	global_load_dwordx4 v[134:137], v1, s[4:5] offset:2064
	global_load_dwordx4 v[138:141], v2, s[4:5]
	global_load_dwordx4 v[142:145], v2, s[4:5] offset:16
	s_add_u32 s4, s4, 0x1800
	s_addc_u32 s5, s5, 0
	s_add_i32 s12, s11, 2
	s_cmp_lt_u32 s12, 0x4000
	s_cselect_b32 s29, s3, s13
	s_and_b32 s27, s12, s29
	v_pk_mul_f32 v[234:235], v[20:21], v[52:53]
	v_pk_mul_f32 v[236:237], v[22:23], v[54:55]
	v_pk_mul_f32 v[238:239], v[24:25], v[56:57]
	v_pk_mul_f32 v[240:241], v[26:27], v[58:59]
	v_pk_mul_f32 v[242:243], v[28:29], v[60:61]
	v_pk_mul_f32 v[244:245], v[30:31], v[62:63]
	v_pk_mul_f32 v[246:247], v[32:33], v[64:65]
	v_pk_mul_f32 v[248:249], v[34:35], v[66:67]
	s_cmp_eq_u32 s27, 0
	s_cbranch_scc1 .Lcg9_np2
	v_pk_fma_f32 v[234:235], v[4:5], v[98:99], v[234:235]
	v_pk_fma_f32 v[236:237], v[6:7], v[100:101], v[236:237]
	v_pk_fma_f32 v[238:239], v[8:9], v[102:103], v[238:239]
	v_pk_fma_f32 v[240:241], v[10:11], v[104:105], v[240:241]
	v_pk_fma_f32 v[242:243], v[12:13], v[106:107], v[242:243]
	v_pk_fma_f32 v[244:245], v[14:15], v[108:109], v[244:245]
	v_pk_fma_f32 v[246:247], v[16:17], v[110:111], v[246:247]
	v_pk_fma_f32 v[248:249], v[18:19], v[112:113], v[248:249]

; __device__ __forceinline__ unsigned cvt_pk_bf16(float lo, float hi) { unsigned r; asm volatile("v_cvt_pk_bf16_f32 %0, %1, %2" : "=v"(r) : "v"(lo), "v"(hi)); return r; }
; __device__ __forceinline__ float bflo(unsigned w) { return __uint_as_float(w << 16); }
; __device__ __forceinline__ float bfhi(unsigned w) { return __uint_as_float(w & 0xffff0000u); }
; __device__ __forceinline__ void convgate_phase(const bf16_t* U, bf16_t* H, int rows, const float* ck, int gw, int NGW, int lane) {
;     for (int row = gw; row < rows; row += NGW) {
;         const bool lat = row < ML; const int t = lat ? (row & (SEQ - 1)) : ((row - ML) & (CL - 1)); const int L = lat ? SEQ : CL;
;         const bool hasp = t > 0, hasn = t < L - 1;
;         const bf16_t* ur = U + (size_t)row * 3072;
;         u32x4 bq[2], cq[2], vq[2], cp[2], vp[2], cn[2], vn[2];
; #pragma unroll
;         for (int hf = 0; hf < 2; ++hf) {
;             const int c0 = lane * 16 + hf * 8;
;             bq[hf] = *(const u32x4*)(ur + c0); cq[hf] = *(const u32x4*)(ur + 1024 + c0); vq[hf] = *(const u32x4*)(ur + 2048 + c0);
;             cp[hf] = (u32x4){0, 0, 0, 0}; vp[hf] = cp[hf]; cn[hf] = cp[hf]; vn[hf] = cp[hf];
;             if (hasp) { cp[hf] = *(const u32x4*)(ur - 3072 + 1024 + c0); vp[hf] = *(const u32x4*)(ur - 3072 + 2048 + c0); }
;             if (hasn) { cn[hf] = *(const u32x4*)(ur + 3072 + 1024 + c0); vn[hf] = *(const u32x4*)(ur + 3072 + 2048 + c0); }
;         }
; #pragma unroll
;         for (int hf = 0; hf < 2; ++hf) {
;             const int c0 = lane * 16 + hf * 8;
;             u32x4 ow;
; #pragma unroll
;             for (int e = 0; e < 4; ++e) {
;                 const f32x2 w0 = *(const f32x2*)(ck + c0 + 2 * e), w1 = *(const f32x2*)(ck + D + c0 + 2 * e), w2 = *(const f32x2*)(ck + 2 * D + c0 + 2 * e);
;                 const float lo = bflo(bq[hf][e]) * (w0[0] * (bflo(cp[hf][e]) * bflo(vp[hf][e])) + w1[0] * (bflo(cq[hf][e]) * bflo(vq[hf][e])) + w2[0] * (bflo(cn[hf][e]) * bflo(vn[hf][e])));
;                 const float hi = bfhi(bq[hf][e]) * (w0[1] * (bfhi(cp[hf][e]) * bfhi(vp[hf][e])) + w1[1] * (bfhi(cq[hf][e]) * bfhi(vq[hf][e])) + w2[1] * (bfhi(cn[hf][e]) * bfhi(vn[hf][e])));
;                 ow[e] = cvt_pk_bf16(lo, hi);
;             }
;             *(u32x4*)(H + (size_t)row * D + c0) = ow;
;         }
.Lcg9_nn2:
	v_lshlrev_b32_e32 v202, 16, v226
	v_and_b32_e32 v203, s14, v226
	v_pk_mul_f32 v[234:235], v[234:235], v[202:203]
	v_lshlrev_b32_e32 v206, 16, v227
	v_and_b32_e32 v207, s14, v227
	v_pk_mul_f32 v[236:237], v[236:237], v[206:207]
	v_lshlrev_b32_e32 v210, 16, v228
	v_and_b32_e32 v211, s14, v228
	v_pk_mul_f32 v[238:239], v[238:239], v[210:211]
	v_lshlrev_b32_e32 v202, 16, v229
	v_and_b32_e32 v203, s14, v229
	v_pk_mul_f32 v[240:241], v[240:241], v[202:203]
	v_lshlrev_b32_e32 v206, 16, v230
	v_and_b32_e32 v207, s14, v230
	v_pk_mul_f32 v[242:243], v[242:243], v[206:207]
	v_lshlrev_b32_e32 v210, 16, v231
	v_and_b32_e32 v211, s14, v231
	v_pk_mul_f32 v[244:245], v[244:245], v[210:211]
	v_lshlrev_b32_e32 v202, 16, v232
	v_and_b32_e32 v203, s14, v232
	v_pk_mul_f32 v[246:247], v[246:247], v[202:203]
	v_lshlrev_b32_e32 v206, 16, v233
	v_and_b32_e32 v207, s14, v233
	v_pk_mul_f32 v[248:249], v[248:249], v[206:207]
	v_cvt_pk_bf16_f32 v84, v234, v235
	v_cvt_pk_bf16_f32 v85, v236, v237
	v_cvt_pk_bf16_f32 v86, v238, v239
	v_cvt_pk_bf16_f32 v87, v240, v241
	v_cvt_pk_bf16_f32 v88, v242, v243
	v_cvt_pk_bf16_f32 v89, v244, v245
	v_cvt_pk_bf16_f32 v90, v246, v247
	v_cvt_pk_bf16_f32 v91, v248, v249
	global_store_dwordx4 v1, v[84:87], s[8:9] nt
	global_store_dwordx4 v1, v[88:91], s[8:9] offset:16 nt
	s_add_u32 s8, s8, 0x800
	s_addc_u32 s9, s9, 0
	global_load_dwordx4 v[226:229], v1, s[6:7]
	global_load_dwordx4 v[230:233], v1, s[6:7] offset:16
	s_add_u32 s6, s6, 0x1800
	s_addc_u32 s7, s7, 0
	s_waitcnt vmcnt(16)
	v_lshlrev_b32_e32 v202, 16, v160
	v_and_b32_e32 v203, s14, v160
	v_lshlrev_b32_e32 v204, 16, v168
	v_and_b32_e32 v205, s14, v168
	v_pk_mul_f32 v[98:99], v[202:203], v[204:205]
	v_lshlrev_b32_e32 v206, 16, v161
	v_and_b32_e32 v207, s14, v161
	v_lshlrev_b32_e32 v208, 16, v169
	v_and_b32_e32 v209, s14, v169
	v_pk_mul_f32 v[100:101], v[206:207], v[208:209]
	v_lshlrev_b32_e32 v210, 16, v162
	v_and_b32_e32 v211, s14, v162
	v_lshlrev_b32_e32 v212, 16, v170
	v_and_b32_e32 v213, s14, v170
	v_pk_mul_f32 v[102:103], v[210:211], v[212:213]
	v_lshlrev_b32_e32 v202, 16, v163
	v_and_b32_e32 v203, s14, v163
	v_lshlrev_b32_e32 v204, 16, v171
	v_and_b32_e32 v205, s14, v171
	v_pk_mul_f32 v[104:105], v[202:203], v[204:205]
	v_lshlrev_b32_e32 v206, 16, v164
	v_and_b32_e32 v207, s14, v164
	v_lshlrev_b32_e32 v208, 16, v172
	v_and_b32_e32 v209, s14, v172
	v_pk_mul_f32 v[106:107], v[206:207], v[208:209]
	v_lshlrev_b32_e32 v210, 16, v165
	v_and_b32_e32 v211, s14, v165
	v_lshlrev_b32_e32 v212, 16, v173
	v_and_b32_e32 v213, s14, v173
	v_pk_mul_f32 v[108:109], v[210:211], v[212:213]
	v_lshlrev_b32_e32 v202, 16, v166
	v_and_b32_e32 v203, s14, v166
	v_lshlrev_b32_e32 v204, 16, v174
	v_and_b32_e32 v205, s14, v174
	v_pk_mul_f32 v[110:111], v[202:203], v[204:205]
	v_lshlrev_b32_e32 v206, 16, v167
	v_and_b32_e32 v207, s14, v167
	v_lshlrev_b32_e32 v208, 16, v175
	v_and_b32_e32 v209, s14, v175
	v_pk_mul_f32 v[112:113], v[206:207], v[208:209]
	global_load_dwordx4 v[160:163], v1, s[4:5] offset:2048
	global_load_dwordx4 v[164:167], v1, s[4:5] offset:2064
	global_load_dwordx4 v[168:171], v2, s[4:5]
	global_load_dwordx4 v[172:175], v2, s[4:5] offset:16
	s_add_u32 s4, s4, 0x1800
	s_addc_u32 s5, s5, 0
	s_add_i32 s12, s11, 3
	s_cmp_lt_u32 s12, 0x4000
	s_cselect_b32 s29, s3, s13
	s_and_b32 s27, s12, s29
	v_pk_mul_f32 v[234:235], v[20:21], v[68:69]
	v_pk_mul_f32 v[236:237], v[22:23], v[70:71]
	v_pk_mul_f32 v[238:239], v[24:25], v[72:73]
	v_pk_mul_f32 v[240:241], v[26:27], v[74:75]
	v_pk_mul_f32 v[242:243], v[28:29], v[76:77]
	v_pk_mul_f32 v[244:245], v[30:31], v[78:79]
	v_pk_mul_f32 v[246:247], v[32:33], v[80:81]
	v_pk_mul_f32 v[248:249], v[34:35], v[82:83]
	s_cmp_eq_u32 s27, 0
	s_cbranch_scc1 .Lcg9_np3
	v_pk_fma_f32 v[234:235], v[4:5], v[52:53], v[234:235]
	v_pk_fma_f32 v[236:237], v[6:7], v[54:55], v[236:237]
	v_pk_fma_f32 v[238:239], v[8:9], v[56:57], v[238:239]
	v_pk_fma_f32 v[240:241], v[10:11], v[58:59], v[240:241]
	v_pk_fma_f32 v[242:243], v[12:13], v[60:61], v[242:243]
	v_pk_fma_f32 v[244:245], v[14:15], v[62:63], v[244:245]
	v_pk_fma_f32 v[246:247], v[16:17], v[64:65], v[246:247]
	v_pk_fma_f32 v[248:249], v[18:19], v[66:67], v[248:249]

; __device__ __forceinline__ unsigned cvt_pk_bf16(float lo, float hi) { unsigned r; asm volatile("v_cvt_pk_bf16_f32 %0, %1, %2" : "=v"(r) : "v"(lo), "v"(hi)); return r; }
; __device__ __forceinline__ float bflo(unsigned w) { return __uint_as_float(w << 16); }
; __device__ __forceinline__ float bfhi(unsigned w) { return __uint_as_float(w & 0xffff0000u); }
; __device__ __forceinline__ void convgate_phase(const bf16_t* U, bf16_t* H, int rows, const float* ck, int gw, int NGW, int lane) {
;     for (int row = gw; row < rows; row += NGW) {
;         const bool lat = row < ML; const int t = lat ? (row & (SEQ - 1)) : ((row - ML) & (CL - 1)); const int L = lat ? SEQ : CL;
;         const bool hasp = t > 0, hasn = t < L - 1;
;         const bf16_t* ur = U + (size_t)row * 3072;
;         u32x4 bq[2], cq[2], vq[2], cp[2], vp[2], cn[2], vn[2];
; #pragma unroll
;         for (int hf = 0; hf < 2; ++hf) {
;             const int c0 = lane * 16 + hf * 8;
;             bq[hf] = *(const u32x4*)(ur + c0); cq[hf] = *(const u32x4*)(ur + 1024 + c0); vq[hf] = *(const u32x4*)(ur + 2048 + c0);
;             cp[hf] = (u32x4){0, 0, 0, 0}; vp[hf] = cp[hf]; cn[hf] = cp[hf]; vn[hf] = cp[hf];
;             if (hasp) { cp[hf] = *(const u32x4*)(ur - 3072 + 1024 + c0); vp[hf] = *(const u32x4*)(ur - 3072 + 2048 + c0); }
;             if (hasn) { cn[hf] = *(const u32x4*)(ur + 3072 + 1024 + c0); vn[hf] = *(const u32x4*)(ur + 3072 + 2048 + c0); }
;         }
; #pragma unroll
;         for (int hf = 0; hf < 2; ++hf) {
;             const int c0 = lane * 16 + hf * 8;
;             u32x4 ow;
; #pragma unroll
;             for (int e = 0; e < 4; ++e) {
;                 const f32x2 w0 = *(const f32x2*)(ck + c0 + 2 * e), w1 = *(const f32x2*)(ck + D + c0 + 2 * e), w2 = *(const f32x2*)(ck + 2 * D + c0 + 2 * e);
;                 const float lo = bflo(bq[hf][e]) * (w0[0] * (bflo(cp[hf][e]) * bflo(vp[hf][e])) + w1[0] * (bflo(cq[hf][e]) * bflo(vq[hf][e])) + w2[0] * (bflo(cn[hf][e]) * bflo(vn[hf][e])));
;                 const float hi = bfhi(bq[hf][e]) * (w0[1] * (bfhi(cp[hf][e]) * bfhi(vp[hf][e])) + w1[1] * (bfhi(cq[hf][e]) * bfhi(vq[hf][e])) + w2[1] * (bfhi(cn[hf][e]) * bfhi(vn[hf][e])));
;                 ow[e] = cvt_pk_bf16(lo, hi);
;             }
;             *(u32x4*)(H + (size_t)row * D + c0) = ow;
;         }
.Lcg9_nn3:
	v_lshlrev_b32_e32 v202, 16, v146
	v_and_b32_e32 v203, s14, v146
	v_pk_mul_f32 v[234:235], v[234:235], v[202:203]
	v_lshlrev_b32_e32 v206, 16, v147
	v_and_b32_e32 v207, s14, v147
	v_pk_mul_f32 v[236:237], v[236:237], v[206:207]
	v_lshlrev_b32_e32 v210, 16, v148
	v_and_b32_e32 v211, s14, v148
	v_pk_mul_f32 v[238:239], v[238:239], v[210:211]
	v_lshlrev_b32_e32 v202, 16, v149
	v_and_b32_e32 v203, s14, v149
	v_pk_mul_f32 v[240:241], v[240:241], v[202:203]
	v_lshlrev_b32_e32 v206, 16, v150
	v_and_b32_e32 v207, s14, v150
	v_pk_mul_f32 v[242:243], v[242:243], v[206:207]
	v_lshlrev_b32_e32 v210, 16, v151
	v_and_b32_e32 v211, s14, v151
	v_pk_mul_f32 v[244:245], v[244:245], v[210:211]
	v_lshlrev_b32_e32 v202, 16, v152
	v_and_b32_e32 v203, s14, v152
	v_pk_mul_f32 v[246:247], v[246:247], v[202:203]
	v_lshlrev_b32_e32 v206, 16, v153
	v_and_b32_e32 v207, s14, v153
	v_pk_mul_f32 v[248:249], v[248:249], v[206:207]
	v_cvt_pk_bf16_f32 v84, v234, v235
	v_cvt_pk_bf16_f32 v85, v236, v237
	v_cvt_pk_bf16_f32 v86, v238, v239
	v_cvt_pk_bf16_f32 v87, v240, v241
	v_cvt_pk_bf16_f32 v88, v242, v243
	v_cvt_pk_bf16_f32 v89, v244, v245
	v_cvt_pk_bf16_f32 v90, v246, v247
	v_cvt_pk_bf16_f32 v91, v248, v249
	global_store_dwordx4 v1, v[84:87], s[8:9] nt
	global_store_dwordx4 v1, v[88:91], s[8:9] offset:16 nt
	s_add_u32 s8, s8, 0x800
	s_addc_u32 s9, s9, 0
	global_load_dwordx4 v[146:149], v1, s[6:7]
	global_load_dwordx4 v[150:153], v1, s[6:7] offset:16
	s_add_u32 s6, s6, 0x1800
	s_addc_u32 s7, s7, 0
	s_waitcnt vmcnt(16)
	v_lshlrev_b32_e32 v202, 16, v114
	v_and_b32_e32 v203, s14, v114
	v_lshlrev_b32_e32 v204, 16, v122
	v_and_b32_e32 v205, s14, v122
	v_pk_mul_f32 v[52:53], v[202:203], v[204:205]
	v_lshlrev_b32_e32 v206, 16, v115
	v_and_b32_e32 v207, s14, v115
	v_lshlrev_b32_e32 v208, 16, v123
	v_and_b32_e32 v209, s14, v123
	v_pk_mul_f32 v[54:55], v[206:207], v[208:209]
	v_lshlrev_b32_e32 v210, 16, v116
	v_and_b32_e32 v211, s14, v116
	v_lshlrev_b32_e32 v212, 16, v124
	v_and_b32_e32 v213, s14, v124
	v_pk_mul_f32 v[56:57], v[210:211], v[212:213]
	v_lshlrev_b32_e32 v202, 16, v117
	v_and_b32_e32 v203, s14, v117
	v_lshlrev_b32_e32 v204, 16, v125
	v_and_b32_e32 v205, s14, v125
	v_pk_mul_f32 v[58:59], v[202:203], v[204:205]
	v_lshlrev_b32_e32 v206, 16, v118
	v_and_b32_e32 v207, s14, v118
	v_lshlrev_b32_e32 v208, 16, v126
	v_and_b32_e32 v209, s14, v126
	v_pk_mul_f32 v[60:61], v[206:207], v[208:209]
	v_lshlrev_b32_e32 v210, 16, v119
	v_and_b32_e32 v211, s14, v119
	v_lshlrev_b32_e32 v212, 16, v127
	v_and_b32_e32 v213, s14, v127
	v_pk_mul_f32 v[62:63], v[210:211], v[212:213]
	v_lshlrev_b32_e32 v202, 16, v120
	v_and_b32_e32 v203, s14, v120
	v_lshlrev_b32_e32 v204, 16, v128
	v_and_b32_e32 v205, s14, v128
	v_pk_mul_f32 v[64:65], v[202:203], v[204:205]
	v_lshlrev_b32_e32 v206, 16, v121
	v_and_b32_e32 v207, s14, v121
	v_lshlrev_b32_e32 v208, 16, v129
	v_and_b32_e32 v209, s14, v129
	v_pk_mul_f32 v[66:67], v[206:207], v[208:209]
	global_load_dwordx4 v[114:117], v1, s[4:5] offset:2048
	global_load_dwordx4 v[118:121], v1, s[4:5] offset:2064
	global_load_dwordx4 v[122:125], v2, s[4:5]
	global_load_dwordx4 v[126:129], v2, s[4:5] offset:16
	s_add_u32 s4, s4, 0x1800
	s_addc_u32 s5, s5, 0
	s_add_i32 s12, s11, 4
	s_cmp_lt_u32 s12, 0x4000
	s_cselect_b32 s29, s3, s13
	s_and_b32 s27, s12, s29
	v_pk_mul_f32 v[234:235], v[20:21], v[98:99]
	v_pk_mul_f32 v[236:237], v[22:23], v[100:101]
	v_pk_mul_f32 v[238:239], v[24:25], v[102:103]
	v_pk_mul_f32 v[240:241], v[26:27], v[104:105]
	v_pk_mul_f32 v[242:243], v[28:29], v[106:107]
	v_pk_mul_f32 v[244:245], v[30:31], v[108:109]
	v_pk_mul_f32 v[246:247], v[32:33], v[110:111]
	v_pk_mul_f32 v[248:249], v[34:35], v[112:113]
	s_cmp_eq_u32 s27, 0
	s_cbranch_scc1 .Lcg9_np4
	v_pk_fma_f32 v[234:235], v[4:5], v[68:69], v[234:235]
	v_pk_fma_f32 v[236:237], v[6:7], v[70:71], v[236:237]
	v_pk_fma_f32 v[238:239], v[8:9], v[72:73], v[238:239]
	v_pk_fma_f32 v[240:241], v[10:11], v[74:75], v[240:241]
	v_pk_fma_f32 v[242:243], v[12:13], v[76:77], v[242:243]
	v_pk_fma_f32 v[244:245], v[14:15], v[78:79], v[244:245]
	v_pk_fma_f32 v[246:247], v[16:17], v[80:81], v[246:247]
	v_pk_fma_f32 v[248:249], v[18:19], v[82:83], v[248:249]

; __device__ __forceinline__ unsigned cvt_pk_bf16(float lo, float hi) { unsigned r; asm volatile("v_cvt_pk_bf16_f32 %0, %1, %2" : "=v"(r) : "v"(lo), "v"(hi)); return r; }
; __device__ __forceinline__ float bflo(unsigned w) { return __uint_as_float(w << 16); }
; __device__ __forceinline__ float bfhi(unsigned w) { return __uint_as_float(w & 0xffff0000u); }
; __device__ __forceinline__ void convgate_phase(const bf16_t* U, bf16_t* H, int rows, const float* ck, int gw, int NGW, int lane) {
;     for (int row = gw; row < rows; row += NGW) {
;         const bool lat = row < ML; const int t = lat ? (row & (SEQ - 1)) : ((row - ML) & (CL - 1)); const int L = lat ? SEQ : CL;
;         const bool hasp = t > 0, hasn = t < L - 1;
;         const bf16_t* ur = U + (size_t)row * 3072;
;         u32x4 bq[2], cq[2], vq[2], cp[2], vp[2], cn[2], vn[2];
; #pragma unroll
;         for (int hf = 0; hf < 2; ++hf) {
;             const int c0 = lane * 16 + hf * 8;
;             bq[hf] = *(const u32x4*)(ur + c0); cq[hf] = *(const u32x4*)(ur + 1024 + c0); vq[hf] = *(const u32x4*)(ur + 2048 + c0);
;             cp[hf] = (u32x4){0, 0, 0, 0}; vp[hf] = cp[hf]; cn[hf] = cp[hf]; vn[hf] = cp[hf];
;             if (hasp) { cp[hf] = *(const u32x4*)(ur - 3072 + 1024 + c0); vp[hf] = *(const u32x4*)(ur - 3072 + 2048 + c0); }
;             if (hasn) { cn[hf] = *(const u32x4*)(ur + 3072 + 1024 + c0); vn[hf] = *(const u32x4*)(ur + 3072 + 2048 + c0); }
;         }
; #pragma unroll
;         for (int hf = 0; hf < 2; ++hf) {
;             const int c0 = lane * 16 + hf * 8;
;             u32x4 ow;
; #pragma unroll
;             for (int e = 0; e < 4; ++e) {
;                 const f32x2 w0 = *(const f32x2*)(ck + c0 + 2 * e), w1 = *(const f32x2*)(ck + D + c0 + 2 * e), w2 = *(const f32x2*)(ck + 2 * D + c0 + 2 * e);
;                 const float lo = bflo(bq[hf][e]) * (w0[0] * (bflo(cp[hf][e]) * bflo(vp[hf][e])) + w1[0] * (bflo(cq[hf][e]) * bflo(vq[hf][e])) + w2[0] * (bflo(cn[hf][e]) * bflo(vn[hf][e])));
;                 const float hi = bfhi(bq[hf][e]) * (w0[1] * (bfhi(cp[hf][e]) * bfhi(vp[hf][e])) + w1[1] * (bfhi(cq[hf][e]) * bfhi(vq[hf][e])) + w2[1] * (bfhi(cn[hf][e]) * bfhi(vn[hf][e])));
;                 ow[e] = cvt_pk_bf16(lo, hi);
;             }
;             *(u32x4*)(H + (size_t)row * D + c0) = ow;
;         }
.Lcg9_nn4:
	v_lshlrev_b32_e32 v202, 16, v176
	v_and_b32_e32 v203, s14, v176
	v_pk_mul_f32 v[234:235], v[234:235], v[202:203]
	v_lshlrev_b32_e32 v206, 16, v177
	v_and_b32_e32 v207, s14, v177
	v_pk_mul_f32 v[236:237], v[236:237], v[206:207]
	v_lshlrev_b32_e32 v210, 16, v178
	v_and_b32_e32 v211, s14, v178
	v_pk_mul_f32 v[238:239], v[238:239], v[210:211]
	v_lshlrev_b32_e32 v202, 16, v179
	v_and_b32_e32 v203, s14, v179
	v_pk_mul_f32 v[240:241], v[240:241], v[202:203]
	v_lshlrev_b32_e32 v206, 16, v180
	v_and_b32_e32 v207, s14, v180
	v_pk_mul_f32 v[242:243], v[242:243], v[206:207]
	v_lshlrev_b32_e32 v210, 16, v181
	v_and_b32_e32 v211, s14, v181
	v_pk_mul_f32 v[244:245], v[244:245], v[210:211]
	v_lshlrev_b32_e32 v202, 16, v182
	v_and_b32_e32 v203, s14, v182
	v_pk_mul_f32 v[246:247], v[246:247], v[202:203]
	v_lshlrev_b32_e32 v206, 16, v183
	v_and_b32_e32 v207, s14, v183
	v_pk_mul_f32 v[248:249], v[248:249], v[206:207]
	v_cvt_pk_bf16_f32 v84, v234, v235
	v_cvt_pk_bf16_f32 v85, v236, v237
	v_cvt_pk_bf16_f32 v86, v238, v239
	v_cvt_pk_bf16_f32 v87, v240, v241
	v_cvt_pk_bf16_f32 v88, v242, v243
	v_cvt_pk_bf16_f32 v89, v244, v245
	v_cvt_pk_bf16_f32 v90, v246, v247
	v_cvt_pk_bf16_f32 v91, v248, v249
	global_store_dwordx4 v1, v[84:87], s[8:9] nt
	global_store_dwordx4 v1, v[88:91], s[8:9] offset:16 nt
	s_add_u32 s8, s8, 0x800
	s_addc_u32 s9, s9, 0
	global_load_dwordx4 v[176:179], v1, s[6:7]
	global_load_dwordx4 v[180:183], v1, s[6:7] offset:16
	s_add_u32 s6, s6, 0x1800
	s_addc_u32 s7, s7, 0
	s_waitcnt vmcnt(16)
	v_lshlrev_b32_e32 v202, 16, v130
	v_and_b32_e32 v203, s14, v130
	v_lshlrev_b32_e32 v204, 16, v138
	v_and_b32_e32 v205, s14, v138
	v_pk_mul_f32 v[68:69], v[202:203], v[204:205]
	v_lshlrev_b32_e32 v206, 16, v131
	v_and_b32_e32 v207, s14, v131
	v_lshlrev_b32_e32 v208, 16, v139
	v_and_b32_e32 v209, s14, v139
	v_pk_mul_f32 v[70:71], v[206:207], v[208:209]
	v_lshlrev_b32_e32 v210, 16, v132
	v_and_b32_e32 v211, s14, v132
	v_lshlrev_b32_e32 v212, 16, v140
	v_and_b32_e32 v213, s14, v140
	v_pk_mul_f32 v[72:73], v[210:211], v[212:213]
	v_lshlrev_b32_e32 v202, 16, v133
	v_and_b32_e32 v203, s14, v133
	v_lshlrev_b32_e32 v204, 16, v141
	v_and_b32_e32 v205, s14, v141
	v_pk_mul_f32 v[74:75], v[202:203], v[204:205]
	v_lshlrev_b32_e32 v206, 16, v134
	v_and_b32_e32 v207, s14, v134
	v_lshlrev_b32_e32 v208, 16, v142
	v_and_b32_e32 v209, s14, v142
	v_pk_mul_f32 v[76:77], v[206:207], v[208:209]
	v_lshlrev_b32_e32 v210, 16, v135
	v_and_b32_e32 v211, s14, v135
	v_lshlrev_b32_e32 v212, 16, v143
	v_and_b32_e32 v213, s14, v143
	v_pk_mul_f32 v[78:79], v[210:211], v[212:213]
	v_lshlrev_b32_e32 v202, 16, v136
	v_and_b32_e32 v203, s14, v136
	v_lshlrev_b32_e32 v204, 16, v144
	v_and_b32_e32 v205, s14, v144
	v_pk_mul_f32 v[80:81], v[202:203], v[204:205]
	v_lshlrev_b32_e32 v206, 16, v137
	v_and_b32_e32 v207, s14, v137
	v_lshlrev_b32_e32 v208, 16, v145
	v_and_b32_e32 v209, s14, v145
	v_pk_mul_f32 v[82:83], v[206:207], v[208:209]
	global_load_dwordx4 v[130:133], v1, s[4:5] offset:2048
	global_load_dwordx4 v[134:137], v1, s[4:5] offset:2064
	global_load_dwordx4 v[138:141], v2, s[4:5]
	global_load_dwordx4 v[142:145], v2, s[4:5] offset:16
	s_add_u32 s4, s4, 0x1800
	s_addc_u32 s5, s5, 0
	s_add_i32 s12, s11, 5
	s_cmp_lt_u32 s12, 0x4000
	s_cselect_b32 s29, s3, s13
	s_and_b32 s27, s12, s29
	v_pk_mul_f32 v[234:235], v[20:21], v[52:53]
	v_pk_mul_f32 v[236:237], v[22:23], v[54:55]
	v_pk_mul_f32 v[238:239], v[24:25], v[56:57]
	v_pk_mul_f32 v[240:241], v[26:27], v[58:59]
	v_pk_mul_f32 v[242:243], v[28:29], v[60:61]
	v_pk_mul_f32 v[244:245], v[30:31], v[62:63]
	v_pk_mul_f32 v[246:247], v[32:33], v[64:65]
	v_pk_mul_f32 v[248:249], v[34:35], v[66:67]
	s_cmp_eq_u32 s27, 0
	s_cbranch_scc1 .Lcg9_np5
	v_pk_fma_f32 v[234:235], v[4:5], v[98:99], v[234:235]
	v_pk_fma_f32 v[236:237], v[6:7], v[100:101], v[236:237]
	v_pk_fma_f32 v[238:239], v[8:9], v[102:103], v[238:239]
	v_pk_fma_f32 v[240:241], v[10:11], v[104:105], v[240:241]
	v_pk_fma_f32 v[242:243], v[12:13], v[106:107], v[242:243]
	v_pk_fma_f32 v[244:245], v[14:15], v[108:109], v[244:245]
	v_pk_fma_f32 v[246:247], v[16:17], v[110:111], v[246:247]
	v_pk_fma_f32 v[248:249], v[18:19], v[112:113], v[248:249]

; __device__ __forceinline__ unsigned cvt_pk_bf16(float lo, float hi) { unsigned r; asm volatile("v_cvt_pk_bf16_f32 %0, %1, %2" : "=v"(r) : "v"(lo), "v"(hi)); return r; }
; __device__ __forceinline__ float bflo(unsigned w) { return __uint_as_float(w << 16); }
; __device__ __forceinline__ float bfhi(unsigned w) { return __uint_as_float(w & 0xffff0000u); }
; __device__ __forceinline__ void convgate_phase(const bf16_t* U, bf16_t* H, int rows, const float* ck, int gw, int NGW, int lane) {
;     for (int row = gw; row < rows; row += NGW) {
;         const bool lat = row < ML; const int t = lat ? (row & (SEQ - 1)) : ((row - ML) & (CL - 1)); const int L = lat ? SEQ : CL;
;         const bool hasp = t > 0, hasn = t < L - 1;
;         const bf16_t* ur = U + (size_t)row * 3072;
;         u32x4 bq[2], cq[2], vq[2], cp[2], vp[2], cn[2], vn[2];
; #pragma unroll
;         for (int hf = 0; hf < 2; ++hf) {
;             const int c0 = lane * 16 + hf * 8;
;             bq[hf] = *(const u32x4*)(ur + c0); cq[hf] = *(const u32x4*)(ur + 1024 + c0); vq[hf] = *(const u32x4*)(ur + 2048 + c0);
;             cp[hf] = (u32x4){0, 0, 0, 0}; vp[hf] = cp[hf]; cn[hf] = cp[hf]; vn[hf] = cp[hf];
;             if (hasp) { cp[hf] = *(const u32x4*)(ur - 3072 + 1024 + c0); vp[hf] = *(const u32x4*)(ur - 3072 + 2048 + c0); }
;             if (hasn) { cn[hf] = *(const u32x4*)(ur + 3072 + 1024 + c0); vn[hf] = *(const u32x4*)(ur + 3072 + 2048 + c0); }
;         }
; #pragma unroll
;         for (int hf = 0; hf < 2; ++hf) {
;             const int c0 = lane * 16 + hf * 8;
;             u32x4 ow;
; #pragma unroll
;             for (int e = 0; e < 4; ++e) {
;                 const f32x2 w0 = *(const f32x2*)(ck + c0 + 2 * e), w1 = *(const f32x2*)(ck + D + c0 + 2 * e), w2 = *(const f32x2*)(ck + 2 * D + c0 + 2 * e);
;                 const float lo = bflo(bq[hf][e]) * (w0[0] * (bflo(cp[hf][e]) * bflo(vp[hf][e])) + w1[0] * (bflo(cq[hf][e]) * bflo(vq[hf][e])) + w2[0] * (bflo(cn[hf][e]) * bflo(vn[hf][e])));
;                 const float hi = bfhi(bq[hf][e]) * (w0[1] * (bfhi(cp[hf][e]) * bfhi(vp[hf][e])) + w1[1] * (bfhi(cq[hf][e]) * bfhi(vq[hf][e])) + w2[1] * (bfhi(cn[hf][e]) * bfhi(vn[hf][e])));
;                 ow[e] = cvt_pk_bf16(lo, hi);
;             }
;             *(u32x4*)(H + (size_t)row * D + c0) = ow;
;         }
.Lcg9_nn5:
	v_lshlrev_b32_e32 v202, 16, v226
	v_and_b32_e32 v203, s14, v226
	v_pk_mul_f32 v[234:235], v[234:235], v[202:203]
	v_lshlrev_b32_e32 v206, 16, v227
	v_and_b32_e32 v207, s14, v227
	v_pk_mul_f32 v[236:237], v[236:237], v[206:207]
	v_lshlrev_b32_e32 v210, 16, v228
	v_and_b32_e32 v211, s14, v228
	v_pk_mul_f32 v[238:239], v[238:239], v[210:211]
	v_lshlrev_b32_e32 v202, 16, v229
	v_and_b32_e32 v203, s14, v229
	v_pk_mul_f32 v[240:241], v[240:241], v[202:203]
	v_lshlrev_b32_e32 v206, 16, v230
	v_and_b32_e32 v207, s14, v230
	v_pk_mul_f32 v[242:243], v[242:243], v[206:207]
	v_lshlrev_b32_e32 v210, 16, v231
	v_and_b32_e32 v211, s14, v231
	v_pk_mul_f32 v[244:245], v[244:245], v[210:211]
	v_lshlrev_b32_e32 v202, 16, v232
	v_and_b32_e32 v203, s14, v232
	v_pk_mul_f32 v[246:247], v[246:247], v[202:203]
	v_lshlrev_b32_e32 v206, 16, v233
	v_and_b32_e32 v207, s14, v233
	v_pk_mul_f32 v[248:249], v[248:249], v[206:207]
	v_cvt_pk_bf16_f32 v84, v234, v235
	v_cvt_pk_bf16_f32 v85, v236, v237
	v_cvt_pk_bf16_f32 v86, v238, v239
	v_cvt_pk_bf16_f32 v87, v240, v241
	v_cvt_pk_bf16_f32 v88, v242, v243
	v_cvt_pk_bf16_f32 v89, v244, v245
	v_cvt_pk_bf16_f32 v90, v246, v247
	v_cvt_pk_bf16_f32 v91, v248, v249
	global_store_dwordx4 v1, v[84:87], s[8:9] nt
	global_store_dwordx4 v1, v[88:91], s[8:9] offset:16 nt
	s_add_u32 s8, s8, 0x800
	s_addc_u32 s9, s9, 0
	global_load_dwordx4 v[226:229], v1, s[6:7]
	global_load_dwordx4 v[230:233], v1, s[6:7] offset:16
	s_add_u32 s6, s6, 0x1800
	s_addc_u32 s7, s7, 0
	s_waitcnt vmcnt(16)
	v_lshlrev_b32_e32 v202, 16, v160
	v_and_b32_e32 v203, s14, v160
	v_lshlrev_b32_e32 v204, 16, v168
	v_and_b32_e32 v205, s14, v168
	v_pk_mul_f32 v[98:99], v[202:203], v[204:205]
	v_lshlrev_b32_e32 v206, 16, v161
	v_and_b32_e32 v207, s14, v161
	v_lshlrev_b32_e32 v208, 16, v169
	v_and_b32_e32 v209, s14, v169
	v_pk_mul_f32 v[100:101], v[206:207], v[208:209]
	v_lshlrev_b32_e32 v210, 16, v162
	v_and_b32_e32 v211, s14, v162
	v_lshlrev_b32_e32 v212, 16, v170
	v_and_b32_e32 v213, s14, v170
	v_pk_mul_f32 v[102:103], v[210:211], v[212:213]
	v_lshlrev_b32_e32 v202, 16, v163
	v_and_b32_e32 v203, s14, v163
	v_lshlrev_b32_e32 v204, 16, v171
	v_and_b32_e32 v205, s14, v171
	v_pk_mul_f32 v[104:105], v[202:203], v[204:205]
	v_lshlrev_b32_e32 v206, 16, v164
	v_and_b32_e32 v207, s14, v164
	v_lshlrev_b32_e32 v208, 16, v172
	v_and_b32_e32 v209, s14, v172
	v_pk_mul_f32 v[106:107], v[206:207], v[208:209]
	v_lshlrev_b32_e32 v210, 16, v165
	v_and_b32_e32 v211, s14, v165
	v_lshlrev_b32_e32 v212, 16, v173
	v_and_b32_e32 v213, s14, v173
	v_pk_mul_f32 v[108:109], v[210:211], v[212:213]
	v_lshlrev_b32_e32 v202, 16, v166
	v_and_b32_e32 v203, s14, v166
	v_lshlrev_b32_e32 v204, 16, v174
	v_and_b32_e32 v205, s14, v174
	v_pk_mul_f32 v[110:111], v[202:203], v[204:205]
	v_lshlrev_b32_e32 v206, 16, v167
	v_and_b32_e32 v207, s14, v167
	v_lshlrev_b32_e32 v208, 16, v175
	v_and_b32_e32 v209, s14, v175
	v_pk_mul_f32 v[112:113], v[206:207], v[208:209]
	s_add_i32 s12, s11, 6
	s_cmp_lt_u32 s12, 0x4000
	s_cselect_b32 s29, s3, s13
	s_and_b32 s27, s12, s29
	v_pk_mul_f32 v[234:235], v[20:21], v[68:69]
	v_pk_mul_f32 v[236:237], v[22:23], v[70:71]
	v_pk_mul_f32 v[238:239], v[24:25], v[72:73]
	v_pk_mul_f32 v[240:241], v[26:27], v[74:75]
	v_pk_mul_f32 v[242:243], v[28:29], v[76:77]
	v_pk_mul_f32 v[244:245], v[30:31], v[78:79]
	v_pk_mul_f32 v[246:247], v[32:33], v[80:81]
	v_pk_mul_f32 v[248:249], v[34:35], v[82:83]
	s_cmp_eq_u32 s27, 0
	s_cbranch_scc1 .Lcg9_np6
	v_pk_fma_f32 v[234:235], v[4:5], v[52:53], v[234:235]
	v_pk_fma_f32 v[236:237], v[6:7], v[54:55], v[236:237]
	v_pk_fma_f32 v[238:239], v[8:9], v[56:57], v[238:239]
	v_pk_fma_f32 v[240:241], v[10:11], v[58:59], v[240:241]
	v_pk_fma_f32 v[242:243], v[12:13], v[60:61], v[242:243]
	v_pk_fma_f32 v[244:245], v[14:15], v[62:63], v[244:245]
	v_pk_fma_f32 v[246:247], v[16:17], v[64:65], v[246:247]
	v_pk_fma_f32 v[248:249], v[18:19], v[66:67], v[248:249]

; __device__ __forceinline__ unsigned cvt_pk_bf16(float lo, float hi) { unsigned r; asm volatile("v_cvt_pk_bf16_f32 %0, %1, %2" : "=v"(r) : "v"(lo), "v"(hi)); return r; }
; __device__ __forceinline__ float bflo(unsigned w) { return __uint_as_float(w << 16); }
; __device__ __forceinline__ float bfhi(unsigned w) { return __uint_as_float(w & 0xffff0000u); }
; __device__ __forceinline__ void convgate_phase(const bf16_t* U, bf16_t* H, int rows, const float* ck, int gw, int NGW, int lane) {
;     for (int row = gw; row < rows; row += NGW) {
;         const bool lat = row < ML; const int t = lat ? (row & (SEQ - 1)) : ((row - ML) & (CL - 1)); const int L = lat ? SEQ : CL;
;         const bool hasp = t > 0, hasn = t < L - 1;
;         const bf16_t* ur = U + (size_t)row * 3072;
;         u32x4 bq[2], cq[2], vq[2], cp[2], vp[2], cn[2], vn[2];
; #pragma unroll
;         for (int hf = 0; hf < 2; ++hf) {
;             const int c0 = lane * 16 + hf * 8;
;             bq[hf] = *(const u32x4*)(ur + c0); cq[hf] = *(const u32x4*)(ur + 1024 + c0); vq[hf] = *(const u32x4*)(ur + 2048 + c0);
;             cp[hf] = (u32x4){0, 0, 0, 0}; vp[hf] = cp[hf]; cn[hf] = cp[hf]; vn[hf] = cp[hf];
;             if (hasp) { cp[hf] = *(const u32x4*)(ur - 3072 + 1024 + c0); vp[hf] = *(const u32x4*)(ur - 3072 + 2048 + c0); }
;             if (hasn) { cn[hf] = *(const u32x4*)(ur + 3072 + 1024 + c0); vn[hf] = *(const u32x4*)(ur + 3072 + 2048 + c0); }
;         }
; #pragma unroll
;         for (int hf = 0; hf < 2; ++hf) {
;             const int c0 = lane * 16 + hf * 8;
;             u32x4 ow;
; #pragma unroll
;             for (int e = 0; e < 4; ++e) {
;                 const f32x2 w0 = *(const f32x2*)(ck + c0 + 2 * e), w1 = *(const f32x2*)(ck + D + c0 + 2 * e), w2 = *(const f32x2*)(ck + 2 * D + c0 + 2 * e);
;                 const float lo = bflo(bq[hf][e]) * (w0[0] * (bflo(cp[hf][e]) * bflo(vp[hf][e])) + w1[0] * (bflo(cq[hf][e]) * bflo(vq[hf][e])) + w2[0] * (bflo(cn[hf][e]) * bflo(vn[hf][e])));
;                 const float hi = bfhi(bq[hf][e]) * (w0[1] * (bfhi(cp[hf][e]) * bfhi(vp[hf][e])) + w1[1] * (bfhi(cq[hf][e]) * bfhi(vq[hf][e])) + w2[1] * (bfhi(cn[hf][e]) * bfhi(vn[hf][e])));
;                 ow[e] = cvt_pk_bf16(lo, hi);
;             }
;             *(u32x4*)(H + (size_t)row * D + c0) = ow;
;         }
.Lcg9_nn6:
	v_lshlrev_b32_e32 v202, 16, v146
	v_and_b32_e32 v203, s14, v146
	v_pk_mul_f32 v[234:235], v[234:235], v[202:203]
	v_lshlrev_b32_e32 v206, 16, v147
	v_and_b32_e32 v207, s14, v147
	v_pk_mul_f32 v[236:237], v[236:237], v[206:207]
	v_lshlrev_b32_e32 v210, 16, v148
	v_and_b32_e32 v211, s14, v148
	v_pk_mul_f32 v[238:239], v[238:239], v[210:211]
	v_lshlrev_b32_e32 v202, 16, v149
	v_and_b32_e32 v203, s14, v149
	v_pk_mul_f32 v[240:241], v[240:241], v[202:203]
	v_lshlrev_b32_e32 v206, 16, v150
	v_and_b32_e32 v207, s14, v150
	v_pk_mul_f32 v[242:243], v[242:243], v[206:207]
	v_lshlrev_b32_e32 v210, 16, v151
	v_and_b32_e32 v211, s14, v151
	v_pk_mul_f32 v[244:245], v[244:245], v[210:211]
	v_lshlrev_b32_e32 v202, 16, v152
	v_and_b32_e32 v203, s14, v152
	v_pk_mul_f32 v[246:247], v[246:247], v[202:203]
	v_lshlrev_b32_e32 v206, 16, v153
	v_and_b32_e32 v207, s14, v153
	v_pk_mul_f32 v[248:249], v[248:249], v[206:207]
	v_cvt_pk_bf16_f32 v84, v234, v235
	v_cvt_pk_bf16_f32 v85, v236, v237
	v_cvt_pk_bf16_f32 v86, v238, v239
	v_cvt_pk_bf16_f32 v87, v240, v241
	v_cvt_pk_bf16_f32 v88, v242, v243
	v_cvt_pk_bf16_f32 v89, v244, v245
	v_cvt_pk_bf16_f32 v90, v246, v247
	v_cvt_pk_bf16_f32 v91, v248, v249
	global_store_dwordx4 v1, v[84:87], s[8:9] nt
	global_store_dwordx4 v1, v[88:91], s[8:9] offset:16 nt
	s_add_u32 s8, s8, 0x800
	s_addc_u32 s9, s9, 0
	s_waitcnt vmcnt(10)
	v_lshlrev_b32_e32 v202, 16, v114
	v_and_b32_e32 v203, s14, v114
	v_lshlrev_b32_e32 v204, 16, v122
	v_and_b32_e32 v205, s14, v122
	v_pk_mul_f32 v[52:53], v[202:203], v[204:205]
	v_lshlrev_b32_e32 v206, 16, v115
	v_and_b32_e32 v207, s14, v115
	v_lshlrev_b32_e32 v208, 16, v123
	v_and_b32_e32 v209, s14, v123
	v_pk_mul_f32 v[54:55], v[206:207], v[208:209]
	v_lshlrev_b32_e32 v210, 16, v116
	v_and_b32_e32 v211, s14, v116
	v_lshlrev_b32_e32 v212, 16, v124
	v_and_b32_e32 v213, s14, v124
	v_pk_mul_f32 v[56:57], v[210:211], v[212:213]
	v_lshlrev_b32_e32 v202, 16, v117
	v_and_b32_e32 v203, s14, v117
	v_lshlrev_b32_e32 v204, 16, v125
	v_and_b32_e32 v205, s14, v125
	v_pk_mul_f32 v[58:59], v[202:203], v[204:205]
	v_lshlrev_b32_e32 v206, 16, v118
	v_and_b32_e32 v207, s14, v118
	v_lshlrev_b32_e32 v208, 16, v126
	v_and_b32_e32 v209, s14, v126
	v_pk_mul_f32 v[60:61], v[206:207], v[208:209]
	v_lshlrev_b32_e32 v210, 16, v119
	v_and_b32_e32 v211, s14, v119
	v_lshlrev_b32_e32 v212, 16, v127
	v_and_b32_e32 v213, s14, v127
	v_pk_mul_f32 v[62:63], v[210:211], v[212:213]
	v_lshlrev_b32_e32 v202, 16, v120
	v_and_b32_e32 v203, s14, v120
	v_lshlrev_b32_e32 v204, 16, v128
	v_and_b32_e32 v205, s14, v128
	v_pk_mul_f32 v[64:65], v[202:203], v[204:205]
	v_lshlrev_b32_e32 v206, 16, v121
	v_and_b32_e32 v207, s14, v121
	v_lshlrev_b32_e32 v208, 16, v129
	v_and_b32_e32 v209, s14, v129
	v_pk_mul_f32 v[66:67], v[206:207], v[208:209]
	s_add_i32 s12, s11, 7
	s_cmp_lt_u32 s12, 0x4000
	s_cselect_b32 s29, s3, s13
	s_and_b32 s27, s12, s29
	v_pk_mul_f32 v[234:235], v[20:21], v[98:99]
	v_pk_mul_f32 v[236:237], v[22:23], v[100:101]
	v_pk_mul_f32 v[238:239], v[24:25], v[102:103]
	v_pk_mul_f32 v[240:241], v[26:27], v[104:105]
	v_pk_mul_f32 v[242:243], v[28:29], v[106:107]
	v_pk_mul_f32 v[244:245], v[30:31], v[108:109]
	v_pk_mul_f32 v[246:247], v[32:33], v[110:111]
	v_pk_mul_f32 v[248:249], v[34:35], v[112:113]
	s_cmp_eq_u32 s27, 0
	s_cbranch_scc1 .Lcg9_np7
	v_pk_fma_f32 v[234:235], v[4:5], v[68:69], v[234:235]
	v_pk_fma_f32 v[236:237], v[6:7], v[70:71], v[236:237]
	v_pk_fma_f32 v[238:239], v[8:9], v[72:73], v[238:239]
	v_pk_fma_f32 v[240:241], v[10:11], v[74:75], v[240:241]
	v_pk_fma_f32 v[242:243], v[12:13], v[76:77], v[242:243]
	v_pk_fma_f32 v[244:245], v[14:15], v[78:79], v[244:245]
	v_pk_fma_f32 v[246:247], v[16:17], v[80:81], v[246:247]
	v_pk_fma_f32 v[248:249], v[18:19], v[82:83], v[248:249]

; __device__ __forceinline__ unsigned cvt_pk_bf16(float lo, float hi) { unsigned r; asm volatile("v_cvt_pk_bf16_f32 %0, %1, %2" : "=v"(r) : "v"(lo), "v"(hi)); return r; }
; __device__ __forceinline__ float bflo(unsigned w) { return __uint_as_float(w << 16); }
; __device__ __forceinline__ float bfhi(unsigned w) { return __uint_as_float(w & 0xffff0000u); }
; __device__ __forceinline__ void convgate_phase(const bf16_t* U, bf16_t* H, int rows, const float* ck, int gw, int NGW, int lane) {
;     for (int row = gw; row < rows; row += NGW) {
;         const bool lat = row < ML; const int t = lat ? (row & (SEQ - 1)) : ((row - ML) & (CL - 1)); const int L = lat ? SEQ : CL;
;         const bool hasp = t > 0, hasn = t < L - 1;
;         const bf16_t* ur = U + (size_t)row * 3072;
;         u32x4 bq[2], cq[2], vq[2], cp[2], vp[2], cn[2], vn[2];
; #pragma unroll
;         for (int hf = 0; hf < 2; ++hf) {
;             const int c0 = lane * 16 + hf * 8;
;             bq[hf] = *(const u32x4*)(ur + c0); cq[hf] = *(const u32x4*)(ur + 1024 + c0); vq[hf] = *(const u32x4*)(ur + 2048 + c0);
;             cp[hf] = (u32x4){0, 0, 0, 0}; vp[hf] = cp[hf]; cn[hf] = cp[hf]; vn[hf] = cp[hf];
;             if (hasp) { cp[hf] = *(const u32x4*)(ur - 3072 + 1024 + c0); vp[hf] = *(const u32x4*)(ur - 3072 + 2048 + c0); }
;             if (hasn) { cn[hf] = *(const u32x4*)(ur + 3072 + 1024 + c0); vn[hf] = *(const u32x4*)(ur + 3072 + 2048 + c0); }
;         }
; #pragma unroll
;         for (int hf = 0; hf < 2; ++hf) {
;             const int c0 = lane * 16 + hf * 8;
;             u32x4 ow;
; #pragma unroll
;             for (int e = 0; e < 4; ++e) {
;                 const f32x2 w0 = *(const f32x2*)(ck + c0 + 2 * e), w1 = *(const f32x2*)(ck + D + c0 + 2 * e), w2 = *(const f32x2*)(ck + 2 * D + c0 + 2 * e);
;                 const float lo = bflo(bq[hf][e]) * (w0[0] * (bflo(cp[hf][e]) * bflo(vp[hf][e])) + w1[0] * (bflo(cq[hf][e]) * bflo(vq[hf][e])) + w2[0] * (bflo(cn[hf][e]) * bflo(vn[hf][e])));
;                 const float hi = bfhi(bq[hf][e]) * (w0[1] * (bfhi(cp[hf][e]) * bfhi(vp[hf][e])) + w1[1] * (bfhi(cq[hf][e]) * bfhi(vq[hf][e])) + w2[1] * (bfhi(cn[hf][e]) * bfhi(vn[hf][e])));
;                 ow[e] = cvt_pk_bf16(lo, hi);
;             }
;             *(u32x4*)(H + (size_t)row * D + c0) = ow;
;         }
.Lcg9_nn7:
	v_lshlrev_b32_e32 v202, 16, v176
	v_and_b32_e32 v203, s14, v176
	v_pk_mul_f32 v[234:235], v[234:235], v[202:203]
	v_lshlrev_b32_e32 v206, 16, v177
	v_and_b32_e32 v207, s14, v177
	v_pk_mul_f32 v[236:237], v[236:237], v[206:207]
	v_lshlrev_b32_e32 v210, 16, v178
	v_and_b32_e32 v211, s14, v178
	v_pk_mul_f32 v[238:239], v[238:239], v[210:211]
	v_lshlrev_b32_e32 v202, 16, v179
	v_and_b32_e32 v203, s14, v179
	v_pk_mul_f32 v[240:241], v[240:241], v[202:203]
	v_lshlrev_b32_e32 v206, 16, v180
	v_and_b32_e32 v207, s14, v180
	v_pk_mul_f32 v[242:243], v[242:243], v[206:207]
	v_lshlrev_b32_e32 v210, 16, v181
	v_and_b32_e32 v211, s14, v181
	v_pk_mul_f32 v[244:245], v[244:245], v[210:211]
	v_lshlrev_b32_e32 v202, 16, v182
	v_and_b32_e32 v203, s14, v182
	v_pk_mul_f32 v[246:247], v[246:247], v[202:203]
	v_lshlrev_b32_e32 v206, 16, v183
	v_and_b32_e32 v207, s14, v183
	v_pk_mul_f32 v[248:249], v[248:249], v[206:207]
	v_cvt_pk_bf16_f32 v84, v234, v235
	v_cvt_pk_bf16_f32 v85, v236, v237
	v_cvt_pk_bf16_f32 v86, v238, v239
	v_cvt_pk_bf16_f32 v87, v240, v241
	v_cvt_pk_bf16_f32 v88, v242, v243
	v_cvt_pk_bf16_f32 v89, v244, v245
	v_cvt_pk_bf16_f32 v90, v246, v247
	v_cvt_pk_bf16_f32 v91, v248, v249
	global_store_dwordx4 v1, v[84:87], s[8:9] nt
	global_store_dwordx4 v1, v[88:91], s[8:9] offset:16 nt
	s_add_u32 s8, s8, 0x800
	s_addc_u32 s9, s9, 0
	s_waitcnt vmcnt(4)
	v_lshlrev_b32_e32 v202, 16, v130
	v_and_b32_e32 v203, s14, v130
	v_lshlrev_b32_e32 v204, 16, v138
	v_and_b32_e32 v205, s14, v138
	v_pk_mul_f32 v[68:69], v[202:203], v[204:205]
	v_lshlrev_b32_e32 v206, 16, v131
	v_and_b32_e32 v207, s14, v131
	v_lshlrev_b32_e32 v208, 16, v139
	v_and_b32_e32 v209, s14, v139
	v_pk_mul_f32 v[70:71], v[206:207], v[208:209]
	v_lshlrev_b32_e32 v210, 16, v132
	v_and_b32_e32 v211, s14, v132
	v_lshlrev_b32_e32 v212, 16, v140
	v_and_b32_e32 v213, s14, v140
	v_pk_mul_f32 v[72:73], v[210:211], v[212:213]
	v_lshlrev_b32_e32 v202, 16, v133
	v_and_b32_e32 v203, s14, v133
	v_lshlrev_b32_e32 v204, 16, v141
	v_and_b32_e32 v205, s14, v141
	v_pk_mul_f32 v[74:75], v[202:203], v[204:205]
	v_lshlrev_b32_e32 v206, 16, v134
	v_and_b32_e32 v207, s14, v134
	v_lshlrev_b32_e32 v208, 16, v142
	v_and_b32_e32 v209, s14, v142
	v_pk_mul_f32 v[76:77], v[206:207], v[208:209]
	v_lshlrev_b32_e32 v210, 16, v135
	v_and_b32_e32 v211, s14, v135
	v_lshlrev_b32_e32 v212, 16, v143
	v_and_b32_e32 v213, s14, v143
	v_pk_mul_f32 v[78:79], v[210:211], v[212:213]
	v_lshlrev_b32_e32 v202, 16, v136
	v_and_b32_e32 v203, s14, v136
	v_lshlrev_b32_e32 v204, 16, v144
	v_and_b32_e32 v205, s14, v144
	v_pk_mul_f32 v[80:81], v[202:203], v[204:205]
	v_lshlrev_b32_e32 v206, 16, v137
	v_and_b32_e32 v207, s14, v137
	v_lshlrev_b32_e32 v208, 16, v145
	v_and_b32_e32 v209, s14, v145
	v_pk_mul_f32 v[82:83], v[206:207], v[208:209]
	s_add_i32 s12, s11, 8
	s_cmp_lt_u32 s12, 0x4000
	s_cselect_b32 s29, s3, s13
	s_and_b32 s27, s12, s29
	v_pk_mul_f32 v[234:235], v[20:21], v[52:53]
	v_pk_mul_f32 v[236:237], v[22:23], v[54:55]
	v_pk_mul_f32 v[238:239], v[24:25], v[56:57]
	v_pk_mul_f32 v[240:241], v[26:27], v[58:59]
	v_pk_mul_f32 v[242:243], v[28:29], v[60:61]
	v_pk_mul_f32 v[244:245], v[30:31], v[62:63]
	v_pk_mul_f32 v[246:247], v[32:33], v[64:65]
	v_pk_mul_f32 v[248:249], v[34:35], v[66:67]
	s_cmp_eq_u32 s27, 0
	s_cbranch_scc1 .Lcg9_np8
	v_pk_fma_f32 v[234:235], v[4:5], v[98:99], v[234:235]
	v_pk_fma_f32 v[236:237], v[6:7], v[100:101], v[236:237]
	v_pk_fma_f32 v[238:239], v[8:9], v[102:103], v[238:239]
	v_pk_fma_f32 v[240:241], v[10:11], v[104:105], v[240:241]
	v_pk_fma_f32 v[242:243], v[12:13], v[106:107], v[242:243]
	v_pk_fma_f32 v[244:245], v[14:15], v[108:109], v[244:245]
	v_pk_fma_f32 v[246:247], v[16:17], v[110:111], v[246:247]
	v_pk_fma_f32 v[248:249], v[18:19], v[112:113], v[248:249]

; __device__ __forceinline__ unsigned cvt_pk_bf16(float lo, float hi) { unsigned r; asm volatile("v_cvt_pk_bf16_f32 %0, %1, %2" : "=v"(r) : "v"(lo), "v"(hi)); return r; }
; __device__ __forceinline__ float bflo(unsigned w) { return __uint_as_float(w << 16); }
; __device__ __forceinline__ float bfhi(unsigned w) { return __uint_as_float(w & 0xffff0000u); }
; __device__ __forceinline__ void convgate_phase(const bf16_t* U, bf16_t* H, int rows, const float* ck, int gw, int NGW, int lane) {
;     ...
;                 const float lo = bflo(bq[hf][e]) * (w0[0] * (bflo(cp[hf][e]) * bflo(vp[hf][e])) + w1[0] * (bflo(cq[hf][e]) * bflo(vq[hf][e])) + w2[0] * (bflo(cn[hf][e]) * bflo(vn[hf][e])));
;                 const float hi = bfhi(bq[hf][e]) * (w0[1] * (bfhi(cp[hf][e]) * bfhi(vp[hf][e])) + w1[1] * (bfhi(cq[hf][e]) * bfhi(vq[hf][e])) + w2[1] * (bfhi(cn[hf][e]) * bfhi(vn[hf][e])));
;                 ow[e] = cvt_pk_bf16(lo, hi);
;             }
;             *(u32x4*)(H + (size_t)row * D + c0) = ow;
.Lcg9_nn8:
	v_lshlrev_b32_e32 v202, 16, v226
	v_and_b32_e32 v203, s14, v226
	v_pk_mul_f32 v[234:235], v[234:235], v[202:203]
	v_lshlrev_b32_e32 v206, 16, v227
	v_and_b32_e32 v207, s14, v227
	v_pk_mul_f32 v[236:237], v[236:237], v[206:207]
	v_lshlrev_b32_e32 v210, 16, v228
	v_and_b32_e32 v211, s14, v228
	v_pk_mul_f32 v[238:239], v[238:239], v[210:211]
	v_lshlrev_b32_e32 v202, 16, v229
	v_and_b32_e32 v203, s14, v229
	v_pk_mul_f32 v[240:241], v[240:241], v[202:203]
	v_lshlrev_b32_e32 v206, 16, v230
	v_and_b32_e32 v207, s14, v230
	v_pk_mul_f32 v[242:243], v[242:243], v[206:207]
	v_lshlrev_b32_e32 v210, 16, v231
	v_and_b32_e32 v211, s14, v231
	v_pk_mul_f32 v[244:245], v[244:245], v[210:211]
	v_lshlrev_b32_e32 v202, 16, v232
	v_and_b32_e32 v203, s14, v232
	v_pk_mul_f32 v[246:247], v[246:247], v[202:203]
	v_lshlrev_b32_e32 v206, 16, v233
	v_and_b32_e32 v207, s14, v233
	v_pk_mul_f32 v[248:249], v[248:249], v[206:207]
	v_cvt_pk_bf16_f32 v84, v234, v235
	v_cvt_pk_bf16_f32 v85, v236, v237
	v_cvt_pk_bf16_f32 v86, v238, v239
	v_cvt_pk_bf16_f32 v87, v240, v241
	v_cvt_pk_bf16_f32 v88, v242, v243
	v_cvt_pk_bf16_f32 v89, v244, v245
	v_cvt_pk_bf16_f32 v90, v246, v247
	v_cvt_pk_bf16_f32 v91, v248, v249
	global_store_dwordx4 v1, v[84:87], s[8:9] nt
	global_store_dwordx4 v1, v[88:91], s[8:9] offset:16 nt
	s_add_u32 s8, s8, 0x800
	s_addc_u32 s9, s9, 0
	s_branch .Lcg_done

; __device__ __forceinline__ unsigned cvt_pk_bf16(float lo, float hi) { unsigned r; asm volatile("v_cvt_pk_bf16_f32 %0, %1, %2" : "=v"(r) : "v"(lo), "v"(hi)); return r; }
; __device__ __forceinline__ float bflo(unsigned w) { return __uint_as_float(w << 16); }
; __device__ __forceinline__ float bfhi(unsigned w) { return __uint_as_float(w & 0xffff0000u); }
; __device__ __forceinline__ void convgate_phase(const bf16_t* U, bf16_t* H, int rows, const float* ck, int gw, int NGW, int lane) {
;     for (int row = gw; row < rows; row += NGW) {
;         const bool lat = row < ML; const int t = lat ? (row & (SEQ - 1)) : ((row - ML) & (CL - 1)); const int L = lat ? SEQ : CL;
;         const bool hasp = t > 0, hasn = t < L - 1;
;         const bf16_t* ur = U + (size_t)row * 3072;
;         u32x4 bq[2], cq[2], vq[2], cp[2], vp[2], cn[2], vn[2];
; #pragma unroll
;         for (int hf = 0; hf < 2; ++hf) {
;             const int c0 = lane * 16 + hf * 8;
;             bq[hf] = *(const u32x4*)(ur + c0); cq[hf] = *(const u32x4*)(ur + 1024 + c0); vq[hf] = *(const u32x4*)(ur + 2048 + c0);
;             cp[hf] = (u32x4){0, 0, 0, 0}; vp[hf] = cp[hf]; cn[hf] = cp[hf]; vn[hf] = cp[hf];
;             if (hasp) { cp[hf] = *(const u32x4*)(ur - 3072 + 1024 + c0); vp[hf] = *(const u32x4*)(ur - 3072 + 2048 + c0); }
;             if (hasn) { cn[hf] = *(const u32x4*)(ur + 3072 + 1024 + c0); vn[hf] = *(const u32x4*)(ur + 3072 + 2048 + c0); }
;         }
; #pragma unroll
;         for (int hf = 0; hf < 2; ++hf) {
;             const int c0 = lane * 16 + hf * 8;
;             u32x4 ow;
; #pragma unroll
;             for (int e = 0; e < 4; ++e) {
;                 const f32x2 w0 = *(const f32x2*)(ck + c0 + 2 * e), w1 = *(const f32x2*)(ck + D + c0 + 2 * e), w2 = *(const f32x2*)(ck + 2 * D + c0 + 2 * e);
;                 const float lo = bflo(bq[hf][e]) * (w0[0] * (bflo(cp[hf][e]) * bflo(vp[hf][e])) + w1[0] * (bflo(cq[hf][e]) * bflo(vq[hf][e])) + w2[0] * (bflo(cn[hf][e]) * bflo(vn[hf][e])));
;                 const float hi = bfhi(bq[hf][e]) * (w0[1] * (bfhi(cp[hf][e]) * bfhi(vp[hf][e])) + w1[1] * (bfhi(cq[hf][e]) * bfhi(vq[hf][e])) + w2[1] * (bfhi(cn[hf][e]) * bfhi(vn[hf][e])));
;                 ow[e] = cvt_pk_bf16(lo, hi);
;             }
;             *(u32x4*)(H + (size_t)row * D + c0) = ow;
;         }
.Lcg8_nn4:
	v_lshlrev_b32_e32 v202, 16, v176
	v_and_b32_e32 v203, s14, v176
	v_pk_mul_f32 v[234:235], v[234:235], v[202:203]
	v_lshlrev_b32_e32 v206, 16, v177
	v_and_b32_e32 v207, s14, v177
	v_pk_mul_f32 v[236:237], v[236:237], v[206:207]
	v_lshlrev_b32_e32 v210, 16, v178
	v_and_b32_e32 v211, s14, v178
	v_pk_mul_f32 v[238:239], v[238:239], v[210:211]
	v_lshlrev_b32_e32 v202, 16, v179
	v_and_b32_e32 v203, s14, v179
	v_pk_mul_f32 v[240:241], v[240:241], v[202:203]
	v_lshlrev_b32_e32 v206, 16, v180
	v_and_b32_e32 v207, s14, v180
	v_pk_mul_f32 v[242:243], v[242:243], v[206:207]
	v_lshlrev_b32_e32 v210, 16, v181
	v_and_b32_e32 v211, s14, v181
	v_pk_mul_f32 v[244:245], v[244:245], v[210:211]
	v_lshlrev_b32_e32 v202, 16, v182
	v_and_b32_e32 v203, s14, v182
	v_pk_mul_f32 v[246:247], v[246:247], v[202:203]
	v_lshlrev_b32_e32 v206, 16, v183
	v_and_b32_e32 v207, s14, v183
	v_pk_mul_f32 v[248:249], v[248:249], v[206:207]
	v_cvt_pk_bf16_f32 v84, v234, v235
	v_cvt_pk_bf16_f32 v85, v236, v237
	v_cvt_pk_bf16_f32 v86, v238, v239
	v_cvt_pk_bf16_f32 v87, v240, v241
	v_cvt_pk_bf16_f32 v88, v242, v243
	v_cvt_pk_bf16_f32 v89, v244, v245
	v_cvt_pk_bf16_f32 v90, v246, v247
	v_cvt_pk_bf16_f32 v91, v248, v249
	global_store_dwordx4 v1, v[84:87], s[8:9] nt
	global_store_dwordx4 v1, v[88:91], s[8:9] offset:16 nt
	s_add_u32 s8, s8, 0x800
	s_addc_u32 s9, s9, 0
	global_load_dwordx4 v[176:179], v1, s[6:7]
	global_load_dwordx4 v[180:183], v1, s[6:7] offset:16
	s_add_u32 s6, s6, 0x1800
	s_addc_u32 s7, s7, 0
	s_waitcnt vmcnt(16)
	v_lshlrev_b32_e32 v202, 16, v130
	v_and_b32_e32 v203, s14, v130
	v_lshlrev_b32_e32 v204, 16, v138
	v_and_b32_e32 v205, s14, v138
	v_pk_mul_f32 v[68:69], v[202:203], v[204:205]
	v_lshlrev_b32_e32 v206, 16, v131
	v_and_b32_e32 v207, s14, v131
	v_lshlrev_b32_e32 v208, 16, v139
	v_and_b32_e32 v209, s14, v139
	v_pk_mul_f32 v[70:71], v[206:207], v[208:209]
	v_lshlrev_b32_e32 v210, 16, v132
	v_and_b32_e32 v211, s14, v132
	v_lshlrev_b32_e32 v212, 16, v140
	v_and_b32_e32 v213, s14, v140
	v_pk_mul_f32 v[72:73], v[210:211], v[212:213]
	v_lshlrev_b32_e32 v202, 16, v133
	v_and_b32_e32 v203, s14, v133
	v_lshlrev_b32_e32 v204, 16, v141
	v_and_b32_e32 v205, s14, v141
	v_pk_mul_f32 v[74:75], v[202:203], v[204:205]
	v_lshlrev_b32_e32 v206, 16, v134
	v_and_b32_e32 v207, s14, v134
	v_lshlrev_b32_e32 v208, 16, v142
	v_and_b32_e32 v209, s14, v142
	v_pk_mul_f32 v[76:77], v[206:207], v[208:209]
	v_lshlrev_b32_e32 v210, 16, v135
	v_and_b32_e32 v211, s14, v135
	v_lshlrev_b32_e32 v212, 16, v143
	v_and_b32_e32 v213, s14, v143
	v_pk_mul_f32 v[78:79], v[210:211], v[212:213]
	v_lshlrev_b32_e32 v202, 16, v136
	v_and_b32_e32 v203, s14, v136
	v_lshlrev_b32_e32 v204, 16, v144
	v_and_b32_e32 v205, s14, v144
	v_pk_mul_f32 v[80:81], v[202:203], v[204:205]
	v_lshlrev_b32_e32 v206, 16, v137
	v_and_b32_e32 v207, s14, v137
	v_lshlrev_b32_e32 v208, 16, v145
	v_and_b32_e32 v209, s14, v145
	v_pk_mul_f32 v[82:83], v[206:207], v[208:209]
	s_add_i32 s12, s11, 5
	s_cmp_lt_u32 s12, 0x4000
	s_cselect_b32 s29, s3, s13
	s_and_b32 s27, s12, s29
	v_pk_mul_f32 v[234:235], v[20:21], v[52:53]
	v_pk_mul_f32 v[236:237], v[22:23], v[54:55]
	v_pk_mul_f32 v[238:239], v[24:25], v[56:57]
	v_pk_mul_f32 v[240:241], v[26:27], v[58:59]
	v_pk_mul_f32 v[242:243], v[28:29], v[60:61]
	v_pk_mul_f32 v[244:245], v[30:31], v[62:63]
	v_pk_mul_f32 v[246:247], v[32:33], v[64:65]
	v_pk_mul_f32 v[248:249], v[34:35], v[66:67]
	s_cmp_eq_u32 s27, 0
	s_cbranch_scc1 .Lcg8_np5
	v_pk_fma_f32 v[234:235], v[4:5], v[98:99], v[234:235]
	v_pk_fma_f32 v[236:237], v[6:7], v[100:101], v[236:237]
	v_pk_fma_f32 v[238:239], v[8:9], v[102:103], v[238:239]
	v_pk_fma_f32 v[240:241], v[10:11], v[104:105], v[240:241]
	v_pk_fma_f32 v[242:243], v[12:13], v[106:107], v[242:243]
	v_pk_fma_f32 v[244:245], v[14:15], v[108:109], v[244:245]
	v_pk_fma_f32 v[246:247], v[16:17], v[110:111], v[246:247]
	v_pk_fma_f32 v[248:249], v[18:19], v[112:113], v[248:249]

; __device__ __forceinline__ unsigned cvt_pk_bf16(float lo, float hi) { unsigned r; asm volatile("v_cvt_pk_bf16_f32 %0, %1, %2" : "=v"(r) : "v"(lo), "v"(hi)); return r; }
; __device__ __forceinline__ float bflo(unsigned w) { return __uint_as_float(w << 16); }
; __device__ __forceinline__ float bfhi(unsigned w) { return __uint_as_float(w & 0xffff0000u); }
; __device__ __forceinline__ void convgate_phase(const bf16_t* U, bf16_t* H, int rows, const float* ck, int gw, int NGW, int lane) {
;     for (int row = gw; row < rows; row += NGW) {
;         const bool lat = row < ML; const int t = lat ? (row & (SEQ - 1)) : ((row - ML) & (CL - 1)); const int L = lat ? SEQ : CL;
;         const bool hasp = t > 0, hasn = t < L - 1;
;         const bf16_t* ur = U + (size_t)row * 3072;
;         u32x4 bq[2], cq[2], vq[2], cp[2], vp[2], cn[2], vn[2];
; #pragma unroll
;         for (int hf = 0; hf < 2; ++hf) {
;             const int c0 = lane * 16 + hf * 8;
;             bq[hf] = *(const u32x4*)(ur + c0); cq[hf] = *(const u32x4*)(ur + 1024 + c0); vq[hf] = *(const u32x4*)(ur + 2048 + c0);
;             cp[hf] = (u32x4){0, 0, 0, 0}; vp[hf] = cp[hf]; cn[hf] = cp[hf]; vn[hf] = cp[hf];
;             if (hasp) { cp[hf] = *(const u32x4*)(ur - 3072 + 1024 + c0); vp[hf] = *(const u32x4*)(ur - 3072 + 2048 + c0); }
;             if (hasn) { cn[hf] = *(const u32x4*)(ur + 3072 + 1024 + c0); vn[hf] = *(const u32x4*)(ur + 3072 + 2048 + c0); }
;         }
; #pragma unroll
;         for (int hf = 0; hf < 2; ++hf) {
;             const int c0 = lane * 16 + hf * 8;
;             u32x4 ow;
; #pragma unroll
;             for (int e = 0; e < 4; ++e) {
;                 const f32x2 w0 = *(const f32x2*)(ck + c0 + 2 * e), w1 = *(const f32x2*)(ck + D + c0 + 2 * e), w2 = *(const f32x2*)(ck + 2 * D + c0 + 2 * e);
;                 const float lo = bflo(bq[hf][e]) * (w0[0] * (bflo(cp[hf][e]) * bflo(vp[hf][e])) + w1[0] * (bflo(cq[hf][e]) * bflo(vq[hf][e])) + w2[0] * (bflo(cn[hf][e]) * bflo(vn[hf][e])));
;                 const float hi = bfhi(bq[hf][e]) * (w0[1] * (bfhi(cp[hf][e]) * bfhi(vp[hf][e])) + w1[1] * (bfhi(cq[hf][e]) * bfhi(vq[hf][e])) + w2[1] * (bfhi(cn[hf][e]) * bfhi(vn[hf][e])));
;                 ow[e] = cvt_pk_bf16(lo, hi);
;             }
;             *(u32x4*)(H + (size_t)row * D + c0) = ow;
;         }
.Lcg8_nn5:
	v_lshlrev_b32_e32 v202, 16, v226
	v_and_b32_e32 v203, s14, v226
	v_pk_mul_f32 v[234:235], v[234:235], v[202:203]
	v_lshlrev_b32_e32 v206, 16, v227
	v_and_b32_e32 v207, s14, v227
	v_pk_mul_f32 v[236:237], v[236:237], v[206:207]
	v_lshlrev_b32_e32 v210, 16, v228
	v_and_b32_e32 v211, s14, v228
	v_pk_mul_f32 v[238:239], v[238:239], v[210:211]
	v_lshlrev_b32_e32 v202, 16, v229
	v_and_b32_e32 v203, s14, v229
	v_pk_mul_f32 v[240:241], v[240:241], v[202:203]
	v_lshlrev_b32_e32 v206, 16, v230
	v_and_b32_e32 v207, s14, v230
	v_pk_mul_f32 v[242:243], v[242:243], v[206:207]
	v_lshlrev_b32_e32 v210, 16, v231
	v_and_b32_e32 v211, s14, v231
	v_pk_mul_f32 v[244:245], v[244:245], v[210:211]
	v_lshlrev_b32_e32 v202, 16, v232
	v_and_b32_e32 v203, s14, v232
	v_pk_mul_f32 v[246:247], v[246:247], v[202:203]
	v_lshlrev_b32_e32 v206, 16, v233
	v_and_b32_e32 v207, s14, v233
	v_pk_mul_f32 v[248:249], v[248:249], v[206:207]
	v_cvt_pk_bf16_f32 v84, v234, v235
	v_cvt_pk_bf16_f32 v85, v236, v237
	v_cvt_pk_bf16_f32 v86, v238, v239
	v_cvt_pk_bf16_f32 v87, v240, v241
	v_cvt_pk_bf16_f32 v88, v242, v243
	v_cvt_pk_bf16_f32 v89, v244, v245
	v_cvt_pk_bf16_f32 v90, v246, v247
	v_cvt_pk_bf16_f32 v91, v248, v249
	global_store_dwordx4 v1, v[84:87], s[8:9] nt
	global_store_dwordx4 v1, v[88:91], s[8:9] offset:16 nt
	s_add_u32 s8, s8, 0x800
	s_addc_u32 s9, s9, 0
	s_waitcnt vmcnt(10)
	v_lshlrev_b32_e32 v202, 16, v160
	v_and_b32_e32 v203, s14, v160
	v_lshlrev_b32_e32 v204, 16, v168
	v_and_b32_e32 v205, s14, v168
	v_pk_mul_f32 v[98:99], v[202:203], v[204:205]
	v_lshlrev_b32_e32 v206, 16, v161
	v_and_b32_e32 v207, s14, v161
	v_lshlrev_b32_e32 v208, 16, v169
	v_and_b32_e32 v209, s14, v169
	v_pk_mul_f32 v[100:101], v[206:207], v[208:209]
	v_lshlrev_b32_e32 v210, 16, v162
	v_and_b32_e32 v211, s14, v162
	v_lshlrev_b32_e32 v212, 16, v170
	v_and_b32_e32 v213, s14, v170
	v_pk_mul_f32 v[102:103], v[210:211], v[212:213]
	v_lshlrev_b32_e32 v202, 16, v163
	v_and_b32_e32 v203, s14, v163
	v_lshlrev_b32_e32 v204, 16, v171
	v_and_b32_e32 v205, s14, v171
	v_pk_mul_f32 v[104:105], v[202:203], v[204:205]
	v_lshlrev_b32_e32 v206, 16, v164
	v_and_b32_e32 v207, s14, v164
	v_lshlrev_b32_e32 v208, 16, v172
	v_and_b32_e32 v209, s14, v172
	v_pk_mul_f32 v[106:107], v[206:207], v[208:209]
	v_lshlrev_b32_e32 v210, 16, v165
	v_and_b32_e32 v211, s14, v165
	v_lshlrev_b32_e32 v212, 16, v173
	v_and_b32_e32 v213, s14, v173
	v_pk_mul_f32 v[108:109], v[210:211], v[212:213]
	v_lshlrev_b32_e32 v202, 16, v166
	v_and_b32_e32 v203, s14, v166
	v_lshlrev_b32_e32 v204, 16, v174
	v_and_b32_e32 v205, s14, v174
	v_pk_mul_f32 v[110:111], v[202:203], v[204:205]
	v_lshlrev_b32_e32 v206, 16, v167
	v_and_b32_e32 v207, s14, v167
	v_lshlrev_b32_e32 v208, 16, v175
	v_and_b32_e32 v209, s14, v175
	v_pk_mul_f32 v[112:113], v[206:207], v[208:209]
	s_add_i32 s12, s11, 6
	s_cmp_lt_u32 s12, 0x4000
	s_cselect_b32 s29, s3, s13
	s_and_b32 s27, s12, s29
	v_pk_mul_f32 v[234:235], v[20:21], v[68:69]
	v_pk_mul_f32 v[236:237], v[22:23], v[70:71]
	v_pk_mul_f32 v[238:239], v[24:25], v[72:73]
	v_pk_mul_f32 v[240:241], v[26:27], v[74:75]
	v_pk_mul_f32 v[242:243], v[28:29], v[76:77]
	v_pk_mul_f32 v[244:245], v[30:31], v[78:79]
	v_pk_mul_f32 v[246:247], v[32:33], v[80:81]
	v_pk_mul_f32 v[248:249], v[34:35], v[82:83]
	s_cmp_eq_u32 s27, 0
	s_cbranch_scc1 .Lcg8_np6
	v_pk_fma_f32 v[234:235], v[4:5], v[52:53], v[234:235]
	v_pk_fma_f32 v[236:237], v[6:7], v[54:55], v[236:237]
	v_pk_fma_f32 v[238:239], v[8:9], v[56:57], v[238:239]
	v_pk_fma_f32 v[240:241], v[10:11], v[58:59], v[240:241]
	v_pk_fma_f32 v[242:243], v[12:13], v[60:61], v[242:243]
	v_pk_fma_f32 v[244:245], v[14:15], v[62:63], v[244:245]
	v_pk_fma_f32 v[246:247], v[16:17], v[64:65], v[246:247]
	v_pk_fma_f32 v[248:249], v[18:19], v[66:67], v[248:249]

; __device__ __forceinline__ unsigned cvt_pk_bf16(float lo, float hi) { unsigned r; asm volatile("v_cvt_pk_bf16_f32 %0, %1, %2" : "=v"(r) : "v"(lo), "v"(hi)); return r; }
; __device__ __forceinline__ float bflo(unsigned w) { return __uint_as_float(w << 16); }
; __device__ __forceinline__ float bfhi(unsigned w) { return __uint_as_float(w & 0xffff0000u); }
; __device__ __forceinline__ void convgate_phase(const bf16_t* U, bf16_t* H, int rows, const float* ck, int gw, int NGW, int lane) {
;     for (int row = gw; row < rows; row += NGW) {
;         const bool lat = row < ML; const int t = lat ? (row & (SEQ - 1)) : ((row - ML) & (CL - 1)); const int L = lat ? SEQ : CL;
;         const bool hasp = t > 0, hasn = t < L - 1;
;         const bf16_t* ur = U + (size_t)row * 3072;
;         u32x4 bq[2], cq[2], vq[2], cp[2], vp[2], cn[2], vn[2];
; #pragma unroll
;         for (int hf = 0; hf < 2; ++hf) {
;             const int c0 = lane * 16 + hf * 8;
;             bq[hf] = *(const u32x4*)(ur + c0); cq[hf] = *(const u32x4*)(ur + 1024 + c0); vq[hf] = *(const u32x4*)(ur + 2048 + c0);
;             cp[hf] = (u32x4){0, 0, 0, 0}; vp[hf] = cp[hf]; cn[hf] = cp[hf]; vn[hf] = cp[hf];
;             if (hasp) { cp[hf] = *(const u32x4*)(ur - 3072 + 1024 + c0); vp[hf] = *(const u32x4*)(ur - 3072 + 2048 + c0); }
;             if (hasn) { cn[hf] = *(const u32x4*)(ur + 3072 + 1024 + c0); vn[hf] = *(const u32x4*)(ur + 3072 + 2048 + c0); }
;         }
; #pragma unroll
;         for (int hf = 0; hf < 2; ++hf) {
;             const int c0 = lane * 16 + hf * 8;
;             u32x4 ow;
; #pragma unroll
;             for (int e = 0; e < 4; ++e) {
;                 const f32x2 w0 = *(const f32x2*)(ck + c0 + 2 * e), w1 = *(const f32x2*)(ck + D + c0 + 2 * e), w2 = *(const f32x2*)(ck + 2 * D + c0 + 2 * e);
;                 const float lo = bflo(bq[hf][e]) * (w0[0] * (bflo(cp[hf][e]) * bflo(vp[hf][e])) + w1[0] * (bflo(cq[hf][e]) * bflo(vq[hf][e])) + w2[0] * (bflo(cn[hf][e]) * bflo(vn[hf][e])));
;                 const float hi = bfhi(bq[hf][e]) * (w0[1] * (bfhi(cp[hf][e]) * bfhi(vp[hf][e])) + w1[1] * (bfhi(cq[hf][e]) * bfhi(vq[hf][e])) + w2[1] * (bfhi(cn[hf][e]) * bfhi(vn[hf][e])));
;                 ow[e] = cvt_pk_bf16(lo, hi);
;             }
;             *(u32x4*)(H + (size_t)row * D + c0) = ow;
;         }
.Lcg8_nn6:
	v_lshlrev_b32_e32 v202, 16, v146
	v_and_b32_e32 v203, s14, v146
	v_pk_mul_f32 v[234:235], v[234:235], v[202:203]
	v_lshlrev_b32_e32 v206, 16, v147
	v_and_b32_e32 v207, s14, v147
	v_pk_mul_f32 v[236:237], v[236:237], v[206:207]
	v_lshlrev_b32_e32 v210, 16, v148
	v_and_b32_e32 v211, s14, v148
	v_pk_mul_f32 v[238:239], v[238:239], v[210:211]
	v_lshlrev_b32_e32 v202, 16, v149
	v_and_b32_e32 v203, s14, v149
	v_pk_mul_f32 v[240:241], v[240:241], v[202:203]
	v_lshlrev_b32_e32 v206, 16, v150
	v_and_b32_e32 v207, s14, v150
	v_pk_mul_f32 v[242:243], v[242:243], v[206:207]
	v_lshlrev_b32_e32 v210, 16, v151
	v_and_b32_e32 v211, s14, v151
	v_pk_mul_f32 v[244:245], v[244:245], v[210:211]
	v_lshlrev_b32_e32 v202, 16, v152
	v_and_b32_e32 v203, s14, v152
	v_pk_mul_f32 v[246:247], v[246:247], v[202:203]
	v_lshlrev_b32_e32 v206, 16, v153
	v_and_b32_e32 v207, s14, v153
	v_pk_mul_f32 v[248:249], v[248:249], v[206:207]
	v_cvt_pk_bf16_f32 v84, v234, v235
	v_cvt_pk_bf16_f32 v85, v236, v237
	v_cvt_pk_bf16_f32 v86, v238, v239
	v_cvt_pk_bf16_f32 v87, v240, v241
	v_cvt_pk_bf16_f32 v88, v242, v243
	v_cvt_pk_bf16_f32 v89, v244, v245
	v_cvt_pk_bf16_f32 v90, v246, v247
	v_cvt_pk_bf16_f32 v91, v248, v249
	global_store_dwordx4 v1, v[84:87], s[8:9] nt
	global_store_dwordx4 v1, v[88:91], s[8:9] offset:16 nt
	s_add_u32 s8, s8, 0x800
	s_addc_u32 s9, s9, 0
	s_waitcnt vmcnt(4)
	v_lshlrev_b32_e32 v202, 16, v114
	v_and_b32_e32 v203, s14, v114
	v_lshlrev_b32_e32 v204, 16, v122
	v_and_b32_e32 v205, s14, v122
	v_pk_mul_f32 v[52:53], v[202:203], v[204:205]
	v_lshlrev_b32_e32 v206, 16, v115
	v_and_b32_e32 v207, s14, v115
	v_lshlrev_b32_e32 v208, 16, v123
	v_and_b32_e32 v209, s14, v123
	v_pk_mul_f32 v[54:55], v[206:207], v[208:209]
	v_lshlrev_b32_e32 v210, 16, v116
	v_and_b32_e32 v211, s14, v116
	v_lshlrev_b32_e32 v212, 16, v124
	v_and_b32_e32 v213, s14, v124
	v_pk_mul_f32 v[56:57], v[210:211], v[212:213]
	v_lshlrev_b32_e32 v202, 16, v117
	v_and_b32_e32 v203, s14, v117
	v_lshlrev_b32_e32 v204, 16, v125
	v_and_b32_e32 v205, s14, v125
	v_pk_mul_f32 v[58:59], v[202:203], v[204:205]
	v_lshlrev_b32_e32 v206, 16, v118
	v_and_b32_e32 v207, s14, v118
	v_lshlrev_b32_e32 v208, 16, v126
	v_and_b32_e32 v209, s14, v126
	v_pk_mul_f32 v[60:61], v[206:207], v[208:209]
	v_lshlrev_b32_e32 v210, 16, v119
	v_and_b32_e32 v211, s14, v119
	v_lshlrev_b32_e32 v212, 16, v127
	v_and_b32_e32 v213, s14, v127
	v_pk_mul_f32 v[62:63], v[210:211], v[212:213]
	v_lshlrev_b32_e32 v202, 16, v120
	v_and_b32_e32 v203, s14, v120
	v_lshlrev_b32_e32 v204, 16, v128
	v_and_b32_e32 v205, s14, v128
	v_pk_mul_f32 v[64:65], v[202:203], v[204:205]
	v_lshlrev_b32_e32 v206, 16, v121
	v_and_b32_e32 v207, s14, v121
	v_lshlrev_b32_e32 v208, 16, v129
	v_and_b32_e32 v209, s14, v129
	v_pk_mul_f32 v[66:67], v[206:207], v[208:209]
	s_add_i32 s12, s11, 7
	s_cmp_lt_u32 s12, 0x4000
	s_cselect_b32 s29, s3, s13
	s_and_b32 s27, s12, s29
	v_pk_mul_f32 v[234:235], v[20:21], v[98:99]
	v_pk_mul_f32 v[236:237], v[22:23], v[100:101]
	v_pk_mul_f32 v[238:239], v[24:25], v[102:103]
	v_pk_mul_f32 v[240:241], v[26:27], v[104:105]
	v_pk_mul_f32 v[242:243], v[28:29], v[106:107]
	v_pk_mul_f32 v[244:245], v[30:31], v[108:109]
	v_pk_mul_f32 v[246:247], v[32:33], v[110:111]
	v_pk_mul_f32 v[248:249], v[34:35], v[112:113]
	s_cmp_eq_u32 s27, 0
	s_cbranch_scc1 .Lcg8_np7
	v_pk_fma_f32 v[234:235], v[4:5], v[68:69], v[234:235]
	v_pk_fma_f32 v[236:237], v[6:7], v[70:71], v[236:237]
	v_pk_fma_f32 v[238:239], v[8:9], v[72:73], v[238:239]
	v_pk_fma_f32 v[240:241], v[10:11], v[74:75], v[240:241]
	v_pk_fma_f32 v[242:243], v[12:13], v[76:77], v[242:243]
	v_pk_fma_f32 v[244:245], v[14:15], v[78:79], v[244:245]
	v_pk_fma_f32 v[246:247], v[16:17], v[80:81], v[246:247]
	v_pk_fma_f32 v[248:249], v[18:19], v[82:83], v[248:249]

; __device__ __forceinline__ unsigned cvt_pk_bf16(float lo, float hi) { unsigned r; asm volatile("v_cvt_pk_bf16_f32 %0, %1, %2" : "=v"(r) : "v"(lo), "v"(hi)); return r; }
; __device__ __forceinline__ float bflo(unsigned w) { return __uint_as_float(w << 16); }
; __device__ __forceinline__ float bfhi(unsigned w) { return __uint_as_float(w & 0xffff0000u); }
; __device__ __forceinline__ void convgate_phase(const bf16_t* U, bf16_t* H, int rows, const float* ck, int gw, int NGW, int lane) {
;     ...
;                 const float lo = bflo(bq[hf][e]) * (w0[0] * (bflo(cp[hf][e]) * bflo(vp[hf][e])) + w1[0] * (bflo(cq[hf][e]) * bflo(vq[hf][e])) + w2[0] * (bflo(cn[hf][e]) * bflo(vn[hf][e])));
;                 const float hi = bfhi(bq[hf][e]) * (w0[1] * (bfhi(cp[hf][e]) * bfhi(vp[hf][e])) + w1[1] * (bfhi(cq[hf][e]) * bfhi(vq[hf][e])) + w2[1] * (bfhi(cn[hf][e]) * bfhi(vn[hf][e])));
;                 ow[e] = cvt_pk_bf16(lo, hi);
;             }
;             *(u32x4*)(H + (size_t)row * D + c0) = ow;
.Lcg8_nn7:
	v_lshlrev_b32_e32 v202, 16, v176
	v_and_b32_e32 v203, s14, v176
	v_pk_mul_f32 v[234:235], v[234:235], v[202:203]
	v_lshlrev_b32_e32 v206, 16, v177
	v_and_b32_e32 v207, s14, v177
	v_pk_mul_f32 v[236:237], v[236:237], v[206:207]
	v_lshlrev_b32_e32 v210, 16, v178
	v_and_b32_e32 v211, s14, v178
	v_pk_mul_f32 v[238:239], v[238:239], v[210:211]
	v_lshlrev_b32_e32 v202, 16, v179
	v_and_b32_e32 v203, s14, v179
	v_pk_mul_f32 v[240:241], v[240:241], v[202:203]
	v_lshlrev_b32_e32 v206, 16, v180
	v_and_b32_e32 v207, s14, v180
	v_pk_mul_f32 v[242:243], v[242:243], v[206:207]
	v_lshlrev_b32_e32 v210, 16, v181
	v_and_b32_e32 v211, s14, v181
	v_pk_mul_f32 v[244:245], v[244:245], v[210:211]
	v_lshlrev_b32_e32 v202, 16, v182
	v_and_b32_e32 v203, s14, v182
	v_pk_mul_f32 v[246:247], v[246:247], v[202:203]
	v_lshlrev_b32_e32 v206, 16, v183
	v_and_b32_e32 v207, s14, v183
	v_pk_mul_f32 v[248:249], v[248:249], v[206:207]
	v_cvt_pk_bf16_f32 v84, v234, v235
	v_cvt_pk_bf16_f32 v85, v236, v237
	v_cvt_pk_bf16_f32 v86, v238, v239
	v_cvt_pk_bf16_f32 v87, v240, v241
	v_cvt_pk_bf16_f32 v88, v242, v243
	v_cvt_pk_bf16_f32 v89, v244, v245
	v_cvt_pk_bf16_f32 v90, v246, v247
	v_cvt_pk_bf16_f32 v91, v248, v249
	global_store_dwordx4 v1, v[84:87], s[8:9] nt
	global_store_dwordx4 v1, v[88:91], s[8:9] offset:16 nt
	s_add_u32 s8, s8, 0x800
	s_addc_u32 s9, s9, 0
	s_branch .Lcg_done
